# E30: K-loop LDS-DMA uses SGPR-base addressing (per-DMA 64-bit VALU address add folded away, 46 removed), on E20
# speedup vs baseline: 1.0064x; 1.0060x over previous
.LBB0_200:
	s_add_u32 s4, s0, 0xfffc0080
	s_addc_u32 s5, s1, -1
	s_add_i32 s12, 0, 0x10000
	s_cmp_eq_u32 s41, 12
	s_cselect_b32 s7, s20, s5
	s_cselect_b32 s6, s21, s4
	v_add_u32_e32 v2, s12, v188
	s_cselect_b32 s5, s22, s40
	s_cselect_b32 s4, s23, s37
	s_add_i32 s13, 0, 0x14000
	ds_read_b128 v[132:135], v2
	ds_read_b128 v[136:139], v2 offset:1024
	ds_read_b128 v[140:143], v2 offset:2048
	ds_read_b128 v[144:147], v2 offset:3072
	v_add_u32_e32 v2, s13, v188
	ds_read_b128 v[156:159], v2
	ds_read_b128 v[164:167], v2 offset:1024
	ds_read_b128 v[168:171], v2 offset:2048
	ds_read_b128 v[172:175], v2 offset:3072
	s_add_i32 m0, s85, 0xc000
	ds_read_b128 v[176:179], v189
	ds_read_b128 v[180:183], v189 offset:1024
	ds_read_b128 v[190:193], v189 offset:2048
	ds_read_b128 v[194:197], v189 offset:3072
	ds_read_b128 v[198:201], v189 offset:4096
	ds_read_b128 v[202:205], v189 offset:5120
	ds_read_b128 v[206:209], v189 offset:6144
	ds_read_b128 v[230:233], v189 offset:7168
	global_load_lds_dwordx4 v154, s[0:1]
	s_add_i32 m0, s85, 0xe000
	s_nop 0
	global_load_lds_dwordx4 v162, s[0:1]
	s_waitcnt vmcnt(8)
	s_waitcnt lgkmcnt(0)
	s_barrier
	s_setprio 1
	s_waitcnt lgkmcnt(0)
	v_mfma_f32_16x16x32_bf16 v[128:131], v[132:135], v[176:179], v[128:131]
	v_mfma_f32_16x16x32_bf16 v[124:127], v[140:143], v[176:179], v[124:127]
	v_mfma_f32_16x16x32_bf16 v[112:115], v[132:135], v[190:193], v[112:115]
	v_mfma_f32_16x16x32_bf16 v[108:111], v[140:143], v[190:193], v[108:111]
	v_mfma_f32_16x16x32_bf16 v[96:99], v[132:135], v[198:201], v[96:99]
	v_mfma_f32_16x16x32_bf16 v[92:95], v[140:143], v[198:201], v[92:95]
	v_mfma_f32_16x16x32_bf16 v[80:83], v[132:135], v[206:209], v[80:83]
	v_mfma_f32_16x16x32_bf16 v[76:79], v[140:143], v[206:209], v[76:79]
	v_mfma_f32_16x16x32_bf16 v[128:131], v[136:139], v[180:183], v[128:131]
	v_mfma_f32_16x16x32_bf16 v[124:127], v[144:147], v[180:183], v[124:127]
	v_mfma_f32_16x16x32_bf16 v[112:115], v[136:139], v[194:197], v[112:115]
	v_mfma_f32_16x16x32_bf16 v[108:111], v[144:147], v[194:197], v[108:111]
	v_mfma_f32_16x16x32_bf16 v[96:99], v[136:139], v[202:205], v[96:99]
	v_mfma_f32_16x16x32_bf16 v[92:95], v[144:147], v[202:205], v[92:95]
	v_mfma_f32_16x16x32_bf16 v[80:83], v[136:139], v[230:233], v[80:83]
	v_mfma_f32_16x16x32_bf16 v[76:79], v[144:147], v[230:233], v[76:79]
	s_setprio 0
	s_setprio 1
	v_mfma_f32_16x16x32_bf16 v[120:123], v[156:159], v[176:179], v[120:123]
	v_mfma_f32_16x16x32_bf16 v[116:119], v[168:171], v[176:179], v[116:119]
	v_mfma_f32_16x16x32_bf16 v[104:107], v[156:159], v[190:193], v[104:107]
	v_mfma_f32_16x16x32_bf16 v[100:103], v[168:171], v[190:193], v[100:103]
	v_mfma_f32_16x16x32_bf16 v[88:91], v[156:159], v[198:201], v[88:91]
	v_mfma_f32_16x16x32_bf16 v[84:87], v[168:171], v[198:201], v[84:87]
	v_mfma_f32_16x16x32_bf16 v[72:75], v[156:159], v[206:209], v[72:75]
	v_mfma_f32_16x16x32_bf16 v[68:71], v[168:171], v[206:209], v[68:71]
	v_mfma_f32_16x16x32_bf16 v[120:123], v[164:167], v[180:183], v[120:123]
	v_mfma_f32_16x16x32_bf16 v[116:119], v[172:175], v[180:183], v[116:119]
	v_mfma_f32_16x16x32_bf16 v[104:107], v[164:167], v[194:197], v[104:107]
	v_mfma_f32_16x16x32_bf16 v[100:103], v[172:175], v[194:197], v[100:103]
	v_mfma_f32_16x16x32_bf16 v[88:91], v[164:167], v[202:205], v[88:91]
	v_mfma_f32_16x16x32_bf16 v[84:87], v[172:175], v[202:205], v[84:87]
	v_mfma_f32_16x16x32_bf16 v[72:75], v[164:167], v[230:233], v[72:75]
	v_mfma_f32_16x16x32_bf16 v[68:71], v[172:175], v[230:233], v[68:71]
	s_setprio 0
	s_barrier
	s_add_i32 s12, s12, s24
	v_lshl_add_u64 v[160:161], s[4:5], 0, v[148:149]
	s_mov_b32 m0, s12
	ds_read_b128 v[176:179], v189 offset:16384
	ds_read_b128 v[180:183], v189 offset:17408
	ds_read_b128 v[190:193], v189 offset:18432
	ds_read_b128 v[194:197], v189 offset:19456
	ds_read_b128 v[198:201], v189 offset:20480
	ds_read_b128 v[202:205], v189 offset:21504
	ds_read_b128 v[206:209], v189 offset:22528
	ds_read_b128 v[230:233], v189 offset:23552
	global_load_lds_dwordx4 v[160:161], off
	s_add_i32 m0, s12, 0x2000
	s_add_u32 vcc_lo, s4, 0x10000
	v_lshl_add_u64 v[184:185], s[4:5], 0, v[152:153]
	s_addc_u32 vcc_hi, s5, 0
	s_add_i32 s12, s13, s24
	global_load_lds_dwordx4 v[184:185], off
	s_mov_b32 m0, s12
	v_lshl_add_u64 v[240:241], s[6:7], 0, v[150:151]
	global_load_lds_dwordx4 v148, vcc
	s_add_i32 m0, s12, 0x2000
	s_nop 0
	global_load_lds_dwordx4 v152, vcc
	v_lshl_add_u64 v[234:235], s[6:7], 0, v[0:1]
	s_mov_b32 m0, s85
	s_nop 0
	global_load_lds_dwordx4 v[234:235], off
	s_mov_b32 m0, s87
	s_nop 0
	global_load_lds_dwordx4 v[240:241], off
	s_waitcnt vmcnt(8)
	s_waitcnt lgkmcnt(0)
	s_barrier
	s_setprio 1
	s_waitcnt lgkmcnt(0)
	v_mfma_f32_16x16x32_bf16 v[64:67], v[132:135], v[176:179], v[64:67]
	v_mfma_f32_16x16x32_bf16 v[60:63], v[140:143], v[176:179], v[60:63]
	v_mfma_f32_16x16x32_bf16 v[48:51], v[132:135], v[190:193], v[48:51]
	v_mfma_f32_16x16x32_bf16 v[44:47], v[140:143], v[190:193], v[44:47]
	v_mfma_f32_16x16x32_bf16 v[32:35], v[132:135], v[198:201], v[32:35]
	v_mfma_f32_16x16x32_bf16 v[28:31], v[140:143], v[198:201], v[28:31]
	v_mfma_f32_16x16x32_bf16 v[16:19], v[132:135], v[206:209], v[16:19]
	v_mfma_f32_16x16x32_bf16 v[12:15], v[140:143], v[206:209], v[12:15]
	v_mfma_f32_16x16x32_bf16 v[64:67], v[136:139], v[180:183], v[64:67]
	v_mfma_f32_16x16x32_bf16 v[60:63], v[144:147], v[180:183], v[60:63]
	v_mfma_f32_16x16x32_bf16 v[48:51], v[136:139], v[194:197], v[48:51]
	v_mfma_f32_16x16x32_bf16 v[44:47], v[144:147], v[194:197], v[44:47]
	v_mfma_f32_16x16x32_bf16 v[32:35], v[136:139], v[202:205], v[32:35]
	v_mfma_f32_16x16x32_bf16 v[28:31], v[144:147], v[202:205], v[28:31]
	v_mfma_f32_16x16x32_bf16 v[16:19], v[136:139], v[230:233], v[16:19]
	v_mfma_f32_16x16x32_bf16 v[12:15], v[144:147], v[230:233], v[12:15]
	s_setprio 0
	s_setprio 1
	v_mfma_f32_16x16x32_bf16 v[56:59], v[156:159], v[176:179], v[56:59]
	v_mfma_f32_16x16x32_bf16 v[52:55], v[168:171], v[176:179], v[52:55]
	v_mfma_f32_16x16x32_bf16 v[40:43], v[156:159], v[190:193], v[40:43]
	v_mfma_f32_16x16x32_bf16 v[36:39], v[168:171], v[190:193], v[36:39]
	v_mfma_f32_16x16x32_bf16 v[24:27], v[156:159], v[198:201], v[24:27]
	v_mfma_f32_16x16x32_bf16 v[20:23], v[168:171], v[198:201], v[20:23]
	v_mfma_f32_16x16x32_bf16 v[8:11], v[156:159], v[206:209], v[8:11]
	v_mfma_f32_16x16x32_bf16 v[4:7], v[168:171], v[206:209], v[4:7]
	v_mfma_f32_16x16x32_bf16 v[56:59], v[164:167], v[180:183], v[56:59]
	v_mfma_f32_16x16x32_bf16 v[52:55], v[172:175], v[180:183], v[52:55]
	v_mfma_f32_16x16x32_bf16 v[40:43], v[164:167], v[194:197], v[40:43]
	v_mfma_f32_16x16x32_bf16 v[36:39], v[172:175], v[194:197], v[36:39]
	v_mfma_f32_16x16x32_bf16 v[24:27], v[164:167], v[202:205], v[24:27]
	v_mfma_f32_16x16x32_bf16 v[20:23], v[172:175], v[202:205], v[20:23]
	v_mfma_f32_16x16x32_bf16 v[8:11], v[164:167], v[230:233], v[8:11]
	v_mfma_f32_16x16x32_bf16 v[4:7], v[172:175], v[230:233], v[4:7]
	s_setprio 0
	s_barrier
	s_add_i32 s12, 0, 0x18000
	v_add_u32_e32 v2, s12, v188
	s_add_i32 s13, 0, 0x1c000
	ds_read_b128 v[132:135], v2
	ds_read_b128 v[136:139], v2 offset:1024
	ds_read_b128 v[140:143], v2 offset:2048
	ds_read_b128 v[144:147], v2 offset:3072
	v_add_u32_e32 v2, s13, v188
	ds_read_b128 v[156:159], v2
	ds_read_b128 v[164:167], v2 offset:1024
	ds_read_b128 v[168:171], v2 offset:2048
	ds_read_b128 v[172:175], v2 offset:3072
	s_add_u32 s6, s6, 0x40000
	s_addc_u32 s7, s7, 0
	s_mov_b32 m0, s88
	ds_read_b128 v[176:179], v189 offset:32768
	ds_read_b128 v[180:183], v189 offset:33792
	ds_read_b128 v[190:193], v189 offset:34816
	ds_read_b128 v[194:197], v189 offset:35840
	ds_read_b128 v[198:201], v189 offset:36864
	ds_read_b128 v[202:205], v189 offset:37888
	ds_read_b128 v[206:209], v189 offset:38912
	ds_read_b128 v[230:233], v189 offset:39936
	global_load_lds_dwordx4 v0, s[6:7]
	s_mov_b32 m0, s89
	s_nop 0
	global_load_lds_dwordx4 v150, s[6:7]
	s_waitcnt vmcnt(8)
	s_waitcnt lgkmcnt(0)
	s_barrier
	s_setprio 1
	s_waitcnt lgkmcnt(0)
	v_mfma_f32_16x16x32_bf16 v[128:131], v[132:135], v[176:179], v[128:131]
	v_mfma_f32_16x16x32_bf16 v[124:127], v[140:143], v[176:179], v[124:127]
	v_mfma_f32_16x16x32_bf16 v[112:115], v[132:135], v[190:193], v[112:115]
	v_mfma_f32_16x16x32_bf16 v[108:111], v[140:143], v[190:193], v[108:111]
	v_mfma_f32_16x16x32_bf16 v[96:99], v[132:135], v[198:201], v[96:99]
	v_mfma_f32_16x16x32_bf16 v[92:95], v[140:143], v[198:201], v[92:95]
	v_mfma_f32_16x16x32_bf16 v[80:83], v[132:135], v[206:209], v[80:83]
	v_mfma_f32_16x16x32_bf16 v[76:79], v[140:143], v[206:209], v[76:79]
	v_mfma_f32_16x16x32_bf16 v[128:131], v[136:139], v[180:183], v[128:131]
	v_mfma_f32_16x16x32_bf16 v[124:127], v[144:147], v[180:183], v[124:127]
	v_mfma_f32_16x16x32_bf16 v[112:115], v[136:139], v[194:197], v[112:115]
	v_mfma_f32_16x16x32_bf16 v[108:111], v[144:147], v[194:197], v[108:111]
	v_mfma_f32_16x16x32_bf16 v[96:99], v[136:139], v[202:205], v[96:99]
	v_mfma_f32_16x16x32_bf16 v[92:95], v[144:147], v[202:205], v[92:95]
	v_mfma_f32_16x16x32_bf16 v[80:83], v[136:139], v[230:233], v[80:83]
	v_mfma_f32_16x16x32_bf16 v[76:79], v[144:147], v[230:233], v[76:79]
	s_setprio 0
	s_setprio 1
	v_mfma_f32_16x16x32_bf16 v[120:123], v[156:159], v[176:179], v[120:123]
	v_mfma_f32_16x16x32_bf16 v[116:119], v[168:171], v[176:179], v[116:119]
	v_mfma_f32_16x16x32_bf16 v[104:107], v[156:159], v[190:193], v[104:107]
	v_mfma_f32_16x16x32_bf16 v[100:103], v[168:171], v[190:193], v[100:103]
	v_mfma_f32_16x16x32_bf16 v[88:91], v[156:159], v[198:201], v[88:91]
	v_mfma_f32_16x16x32_bf16 v[84:87], v[168:171], v[198:201], v[84:87]
	v_mfma_f32_16x16x32_bf16 v[72:75], v[156:159], v[206:209], v[72:75]
	v_mfma_f32_16x16x32_bf16 v[68:71], v[168:171], v[206:209], v[68:71]
	v_mfma_f32_16x16x32_bf16 v[120:123], v[164:167], v[180:183], v[120:123]
	v_mfma_f32_16x16x32_bf16 v[116:119], v[172:175], v[180:183], v[116:119]
	v_mfma_f32_16x16x32_bf16 v[104:107], v[164:167], v[194:197], v[104:107]
	v_mfma_f32_16x16x32_bf16 v[100:103], v[172:175], v[194:197], v[100:103]
	v_mfma_f32_16x16x32_bf16 v[88:91], v[164:167], v[202:205], v[88:91]
	v_mfma_f32_16x16x32_bf16 v[84:87], v[172:175], v[202:205], v[84:87]
	v_mfma_f32_16x16x32_bf16 v[72:75], v[164:167], v[230:233], v[72:75]
	v_mfma_f32_16x16x32_bf16 v[68:71], v[172:175], v[230:233], v[68:71]
	s_setprio 0
	s_barrier
	s_add_i32 s6, s12, s24
	v_lshl_add_u64 v[160:161], v[160:161], 0, s[26:27]
	s_mov_b32 m0, s6
	ds_read_b128 v[176:179], v189 offset:49152
	ds_read_b128 v[180:183], v189 offset:50176
	ds_read_b128 v[190:193], v189 offset:51200
	ds_read_b128 v[194:197], v189 offset:52224
	ds_read_b128 v[198:201], v189 offset:53248
	ds_read_b128 v[202:205], v189 offset:54272
	ds_read_b128 v[206:209], v189 offset:55296
	ds_read_b128 v[230:233], v189 offset:56320
	global_load_lds_dwordx4 v[160:161], off
	s_add_i32 m0, s6, 0x2000
	s_add_u32 s4, s4, 0x10080
	v_lshl_add_u64 v[160:161], v[184:185], 0, s[26:27]
	s_addc_u32 s5, s5, 0
	s_add_i32 s6, s13, s24
	global_load_lds_dwordx4 v[160:161], off
	s_mov_b32 m0, s6
	s_nop 0
	global_load_lds_dwordx4 v148, s[4:5]
	s_add_i32 m0, s6, 0x2000
	s_nop 0
	global_load_lds_dwordx4 v152, s[4:5]
	v_lshl_add_u64 v[160:161], v[234:235], 0, s[26:27]
	s_mov_b32 m0, s91
	s_nop 0
	global_load_lds_dwordx4 v[160:161], off
	v_lshl_add_u64 v[160:161], v[240:241], 0, s[26:27]
	s_mov_b32 m0, s92
	s_nop 0
	global_load_lds_dwordx4 v[160:161], off
	s_waitcnt vmcnt(8)
	s_waitcnt lgkmcnt(0)
	s_barrier
	s_setprio 1
	s_waitcnt lgkmcnt(0)
	v_mfma_f32_16x16x32_bf16 v[64:67], v[132:135], v[176:179], v[64:67]
	v_mfma_f32_16x16x32_bf16 v[60:63], v[140:143], v[176:179], v[60:63]
	v_mfma_f32_16x16x32_bf16 v[48:51], v[132:135], v[190:193], v[48:51]
	v_mfma_f32_16x16x32_bf16 v[44:47], v[140:143], v[190:193], v[44:47]
	v_mfma_f32_16x16x32_bf16 v[32:35], v[132:135], v[198:201], v[32:35]
	v_mfma_f32_16x16x32_bf16 v[28:31], v[140:143], v[198:201], v[28:31]
	v_mfma_f32_16x16x32_bf16 v[16:19], v[132:135], v[206:209], v[16:19]
	v_mfma_f32_16x16x32_bf16 v[12:15], v[140:143], v[206:209], v[12:15]
	v_mfma_f32_16x16x32_bf16 v[64:67], v[136:139], v[180:183], v[64:67]
	v_mfma_f32_16x16x32_bf16 v[60:63], v[144:147], v[180:183], v[60:63]
	v_mfma_f32_16x16x32_bf16 v[48:51], v[136:139], v[194:197], v[48:51]
	v_mfma_f32_16x16x32_bf16 v[44:47], v[144:147], v[194:197], v[44:47]
	v_mfma_f32_16x16x32_bf16 v[32:35], v[136:139], v[202:205], v[32:35]
	v_mfma_f32_16x16x32_bf16 v[28:31], v[144:147], v[202:205], v[28:31]
	v_mfma_f32_16x16x32_bf16 v[16:19], v[136:139], v[230:233], v[16:19]
	v_mfma_f32_16x16x32_bf16 v[12:15], v[144:147], v[230:233], v[12:15]
	s_setprio 0
	s_setprio 1
	v_mfma_f32_16x16x32_bf16 v[56:59], v[156:159], v[176:179], v[56:59]
	v_mfma_f32_16x16x32_bf16 v[52:55], v[168:171], v[176:179], v[52:55]
	v_mfma_f32_16x16x32_bf16 v[40:43], v[156:159], v[190:193], v[40:43]
	v_mfma_f32_16x16x32_bf16 v[36:39], v[168:171], v[190:193], v[36:39]
	v_mfma_f32_16x16x32_bf16 v[24:27], v[156:159], v[198:201], v[24:27]
	v_mfma_f32_16x16x32_bf16 v[20:23], v[168:171], v[198:201], v[20:23]
	v_mfma_f32_16x16x32_bf16 v[8:11], v[156:159], v[206:209], v[8:11]
	v_mfma_f32_16x16x32_bf16 v[4:7], v[168:171], v[206:209], v[4:7]
	v_mfma_f32_16x16x32_bf16 v[56:59], v[164:167], v[180:183], v[56:59]
	v_mfma_f32_16x16x32_bf16 v[52:55], v[172:175], v[180:183], v[52:55]
	v_mfma_f32_16x16x32_bf16 v[40:43], v[164:167], v[194:197], v[40:43]
	v_mfma_f32_16x16x32_bf16 v[36:39], v[172:175], v[194:197], v[36:39]
	v_mfma_f32_16x16x32_bf16 v[24:27], v[164:167], v[202:205], v[24:27]
	v_mfma_f32_16x16x32_bf16 v[20:23], v[172:175], v[202:205], v[20:23]
	v_mfma_f32_16x16x32_bf16 v[8:11], v[164:167], v[230:233], v[8:11]
	v_mfma_f32_16x16x32_bf16 v[4:7], v[172:175], v[230:233], v[4:7]
	s_setprio 0
	s_barrier
	s_add_i32 s41, s41, 2
	s_add_u32 s0, s0, 0x100
	s_addc_u32 s1, s1, 0
	s_add_u32 s37, s37, 0x100
	s_addc_u32 s40, s40, 0
	s_cmp_gt_u32 s41, 13
	s_cbranch_scc0 .LBB0_200
	s_mov_b64 s[26:27], 0x80
	s_and_b64 vcc, exec, s[66:67]
	s_cbranch_vccz .LBB0_203
	s_barrier

.LBB0_1564:
	s_add_u32 s42, s26, s34
	s_addc_u32 s43, s27, s35
	s_add_u32 s40, s42, 0x100
	s_addc_u32 s41, s43, 0
	s_and_b64 s[38:39], s[30:31], exec
	s_cselect_b32 s39, s17, s41
	s_cselect_b32 s38, s63, s40
	s_add_u32 s34, s24, s34
	s_addc_u32 s35, s25, s35
	s_add_u32 s34, s34, 0x100
	s_addc_u32 s35, s35, 0
	s_add_i32 s73, 0, 0x10000
	s_and_b64 s[30:31], s[30:31], exec
	s_cselect_b32 s41, s15, s35
	s_cselect_b32 s40, s64, s34
	s_add_i32 s31, 0, 0x14000
	s_add_u32 s44, s42, 0x10080
	s_addc_u32 s45, s43, 0
	s_add_i32 s72, s73, s52
	s_add_i32 m0, s53, 0xc000
	s_add_i32 s75, s53, 0xe000
	s_add_i32 s69, s72, 0x2000
	v_add_u32_e32 v142, s73, v145
	s_add_u32 s42, s40, 0x10000
	ds_read_b128 v[138:141], v142
	ds_read_b128 v[148:151], v142 offset:1024
	ds_read_b128 v[152:155], v142 offset:2048
	ds_read_b128 v[156:159], v142 offset:3072
	v_add_u32_e32 v142, s31, v145
	s_addc_u32 s43, s41, 0
	s_add_i32 s71, s31, s52
	ds_read_b128 v[160:163], v142
	ds_read_b128 v[164:167], v142 offset:1024
	ds_read_b128 v[168:171], v142 offset:2048
	ds_read_b128 v[172:175], v142 offset:3072
	s_add_i32 s70, s71, 0x2000
	s_add_i32 s68, 0, 0x18000
	s_add_i32 s67, 0, 0x1c000
	s_add_u32 s34, s38, 0x10000
	s_addc_u32 s35, s39, 0
	s_add_i32 s66, s68, s52
	s_add_i32 s65, s66, 0x2000
	s_add_u32 s30, s40, 0x10080
	s_addc_u32 s31, s41, 0
	s_add_i32 s74, s67, s52
	s_add_i32 s73, s74, 0x2000
	ds_read_b128 v[176:179], v146
	ds_read_b128 v[180:183], v146 offset:1024
	ds_read_b128 v[184:187], v146 offset:2048
	ds_read_b128 v[188:191], v146 offset:3072
	ds_read_b128 v[192:195], v146 offset:4096
	ds_read_b128 v[196:199], v146 offset:5120
	ds_read_b128 v[200:203], v146 offset:6144
	ds_read_b128 v[204:207], v146 offset:7168
	global_load_lds_dwordx4 v136, s[44:45]
	s_mov_b32 m0, s75
	s_nop 0
	global_load_lds_dwordx4 v132, s[44:45]
	s_waitcnt vmcnt(8)
	s_waitcnt lgkmcnt(0)
	s_barrier
	s_setprio 1
	s_waitcnt lgkmcnt(0)
	v_mfma_f32_16x16x32_bf16 v[128:131], v[138:141], v[176:179], v[128:131]
	v_mfma_f32_16x16x32_bf16 v[124:127], v[152:155], v[176:179], v[124:127]
	v_mfma_f32_16x16x32_bf16 v[112:115], v[138:141], v[184:187], v[112:115]
	v_mfma_f32_16x16x32_bf16 v[108:111], v[152:155], v[184:187], v[108:111]
	v_mfma_f32_16x16x32_bf16 v[96:99], v[138:141], v[192:195], v[96:99]
	v_mfma_f32_16x16x32_bf16 v[92:95], v[152:155], v[192:195], v[92:95]
	v_mfma_f32_16x16x32_bf16 v[80:83], v[138:141], v[200:203], v[80:83]
	v_mfma_f32_16x16x32_bf16 v[76:79], v[152:155], v[200:203], v[76:79]
	v_mfma_f32_16x16x32_bf16 v[128:131], v[148:151], v[180:183], v[128:131]
	v_mfma_f32_16x16x32_bf16 v[124:127], v[156:159], v[180:183], v[124:127]
	v_mfma_f32_16x16x32_bf16 v[112:115], v[148:151], v[188:191], v[112:115]
	v_mfma_f32_16x16x32_bf16 v[108:111], v[156:159], v[188:191], v[108:111]
	v_mfma_f32_16x16x32_bf16 v[96:99], v[148:151], v[196:199], v[96:99]
	v_mfma_f32_16x16x32_bf16 v[92:95], v[156:159], v[196:199], v[92:95]
	v_mfma_f32_16x16x32_bf16 v[80:83], v[148:151], v[204:207], v[80:83]
	v_mfma_f32_16x16x32_bf16 v[76:79], v[156:159], v[204:207], v[76:79]
	s_setprio 0
	s_setprio 1
	v_mfma_f32_16x16x32_bf16 v[120:123], v[160:163], v[176:179], v[120:123]
	v_mfma_f32_16x16x32_bf16 v[116:119], v[168:171], v[176:179], v[116:119]
	v_mfma_f32_16x16x32_bf16 v[104:107], v[160:163], v[184:187], v[104:107]
	v_mfma_f32_16x16x32_bf16 v[100:103], v[168:171], v[184:187], v[100:103]
	v_mfma_f32_16x16x32_bf16 v[88:91], v[160:163], v[192:195], v[88:91]
	v_mfma_f32_16x16x32_bf16 v[84:87], v[168:171], v[192:195], v[84:87]
	v_mfma_f32_16x16x32_bf16 v[72:75], v[160:163], v[200:203], v[72:75]
	v_mfma_f32_16x16x32_bf16 v[68:71], v[168:171], v[200:203], v[68:71]
	v_mfma_f32_16x16x32_bf16 v[120:123], v[164:167], v[180:183], v[120:123]
	v_mfma_f32_16x16x32_bf16 v[116:119], v[172:175], v[180:183], v[116:119]
	v_mfma_f32_16x16x32_bf16 v[104:107], v[164:167], v[188:191], v[104:107]
	v_mfma_f32_16x16x32_bf16 v[100:103], v[172:175], v[188:191], v[100:103]
	v_mfma_f32_16x16x32_bf16 v[88:91], v[164:167], v[196:199], v[88:91]
	v_mfma_f32_16x16x32_bf16 v[84:87], v[172:175], v[196:199], v[84:87]
	v_mfma_f32_16x16x32_bf16 v[72:75], v[164:167], v[204:207], v[72:75]
	v_mfma_f32_16x16x32_bf16 v[68:71], v[172:175], v[204:207], v[68:71]
	s_setprio 0
	s_barrier
	s_mov_b32 m0, s72
	v_lshl_add_u64 v[142:143], s[40:41], 0, v[134:135]
	ds_read_b128 v[176:179], v146 offset:16384
	ds_read_b128 v[180:183], v146 offset:17408
	ds_read_b128 v[184:187], v146 offset:18432
	ds_read_b128 v[188:191], v146 offset:19456
	ds_read_b128 v[192:195], v146 offset:20480
	ds_read_b128 v[196:199], v146 offset:21504
	ds_read_b128 v[200:203], v146 offset:22528
	ds_read_b128 v[204:207], v146 offset:23552
	global_load_lds_dwordx4 v[142:143], off
	v_lshl_add_u64 v[208:209], s[40:41], 0, v[0:1]
	s_mov_b32 m0, s69
	s_nop 0
	global_load_lds_dwordx4 v[208:209], off
	s_mov_b32 m0, s71
	v_lshl_add_u64 v[232:233], s[38:39], 0, v[132:133]
	global_load_lds_dwordx4 v134, s[42:43]
	s_mov_b32 m0, s70
	s_nop 0
	global_load_lds_dwordx4 v0, s[42:43]
	v_lshl_add_u64 v[230:231], s[38:39], 0, v[136:137]
	s_mov_b32 m0, s53
	s_nop 0
	global_load_lds_dwordx4 v[230:231], off
	s_mov_b32 m0, s54
	s_nop 0
	global_load_lds_dwordx4 v[232:233], off
	s_waitcnt vmcnt(8)
	s_waitcnt lgkmcnt(0)
	s_barrier
	s_setprio 1
	s_waitcnt lgkmcnt(0)
	v_mfma_f32_16x16x32_bf16 v[64:67], v[138:141], v[176:179], v[64:67]
	v_mfma_f32_16x16x32_bf16 v[60:63], v[152:155], v[176:179], v[60:63]
	v_mfma_f32_16x16x32_bf16 v[48:51], v[138:141], v[184:187], v[48:51]
	v_mfma_f32_16x16x32_bf16 v[44:47], v[152:155], v[184:187], v[44:47]
	v_mfma_f32_16x16x32_bf16 v[32:35], v[138:141], v[192:195], v[32:35]
	v_mfma_f32_16x16x32_bf16 v[28:31], v[152:155], v[192:195], v[28:31]
	v_mfma_f32_16x16x32_bf16 v[20:23], v[138:141], v[200:203], v[20:23]
	v_mfma_f32_16x16x32_bf16 v[12:15], v[152:155], v[200:203], v[12:15]
	v_mfma_f32_16x16x32_bf16 v[64:67], v[148:151], v[180:183], v[64:67]
	v_mfma_f32_16x16x32_bf16 v[60:63], v[156:159], v[180:183], v[60:63]
	v_mfma_f32_16x16x32_bf16 v[48:51], v[148:151], v[188:191], v[48:51]
	v_mfma_f32_16x16x32_bf16 v[44:47], v[156:159], v[188:191], v[44:47]
	v_mfma_f32_16x16x32_bf16 v[32:35], v[148:151], v[196:199], v[32:35]
	v_mfma_f32_16x16x32_bf16 v[28:31], v[156:159], v[196:199], v[28:31]
	v_mfma_f32_16x16x32_bf16 v[20:23], v[148:151], v[204:207], v[20:23]
	v_mfma_f32_16x16x32_bf16 v[12:15], v[156:159], v[204:207], v[12:15]
	s_setprio 0
	s_setprio 1
	v_mfma_f32_16x16x32_bf16 v[56:59], v[160:163], v[176:179], v[56:59]
	v_mfma_f32_16x16x32_bf16 v[52:55], v[168:171], v[176:179], v[52:55]
	v_mfma_f32_16x16x32_bf16 v[40:43], v[160:163], v[184:187], v[40:43]
	v_mfma_f32_16x16x32_bf16 v[36:39], v[168:171], v[184:187], v[36:39]
	v_mfma_f32_16x16x32_bf16 v[24:27], v[160:163], v[192:195], v[24:27]
	v_mfma_f32_16x16x32_bf16 v[16:19], v[168:171], v[192:195], v[16:19]
	v_mfma_f32_16x16x32_bf16 v[8:11], v[160:163], v[200:203], v[8:11]
	v_mfma_f32_16x16x32_bf16 v[4:7], v[168:171], v[200:203], v[4:7]
	v_mfma_f32_16x16x32_bf16 v[56:59], v[164:167], v[180:183], v[56:59]
	v_mfma_f32_16x16x32_bf16 v[52:55], v[172:175], v[180:183], v[52:55]
	v_mfma_f32_16x16x32_bf16 v[40:43], v[164:167], v[188:191], v[40:43]
	v_mfma_f32_16x16x32_bf16 v[36:39], v[172:175], v[188:191], v[36:39]
	v_mfma_f32_16x16x32_bf16 v[24:27], v[164:167], v[196:199], v[24:27]
	v_mfma_f32_16x16x32_bf16 v[16:19], v[172:175], v[196:199], v[16:19]
	v_mfma_f32_16x16x32_bf16 v[8:11], v[164:167], v[204:207], v[8:11]
	v_mfma_f32_16x16x32_bf16 v[4:7], v[172:175], v[204:207], v[4:7]
	s_setprio 0
	s_barrier
	v_add_u32_e32 v147, s68, v145
	ds_read_b128 v[138:141], v147
	ds_read_b128 v[148:151], v147 offset:1024
	ds_read_b128 v[152:155], v147 offset:2048
	ds_read_b128 v[156:159], v147 offset:3072
	v_add_u32_e32 v147, s67, v145
	ds_read_b128 v[160:163], v147
	ds_read_b128 v[164:167], v147 offset:1024
	ds_read_b128 v[168:171], v147 offset:2048
	ds_read_b128 v[172:175], v147 offset:3072
	s_mov_b32 m0, s55
	ds_read_b128 v[176:179], v146 offset:32768
	ds_read_b128 v[180:183], v146 offset:33792
	ds_read_b128 v[184:187], v146 offset:34816
	ds_read_b128 v[188:191], v146 offset:35840
	ds_read_b128 v[192:195], v146 offset:36864
	ds_read_b128 v[196:199], v146 offset:37888
	ds_read_b128 v[200:203], v146 offset:38912
	ds_read_b128 v[204:207], v146 offset:39936
	global_load_lds_dwordx4 v136, s[34:35]
	s_mov_b32 m0, s56
	s_nop 0
	global_load_lds_dwordx4 v132, s[34:35]
	s_waitcnt vmcnt(8)
	s_waitcnt lgkmcnt(0)
	s_barrier
	s_setprio 1
	s_waitcnt lgkmcnt(0)
	v_mfma_f32_16x16x32_bf16 v[128:131], v[138:141], v[176:179], v[128:131]
	v_mfma_f32_16x16x32_bf16 v[124:127], v[152:155], v[176:179], v[124:127]
	v_mfma_f32_16x16x32_bf16 v[112:115], v[138:141], v[184:187], v[112:115]
	v_mfma_f32_16x16x32_bf16 v[108:111], v[152:155], v[184:187], v[108:111]
	v_mfma_f32_16x16x32_bf16 v[96:99], v[138:141], v[192:195], v[96:99]
	v_mfma_f32_16x16x32_bf16 v[92:95], v[152:155], v[192:195], v[92:95]
	v_mfma_f32_16x16x32_bf16 v[80:83], v[138:141], v[200:203], v[80:83]
	v_mfma_f32_16x16x32_bf16 v[76:79], v[152:155], v[200:203], v[76:79]
	v_mfma_f32_16x16x32_bf16 v[128:131], v[148:151], v[180:183], v[128:131]
	v_mfma_f32_16x16x32_bf16 v[124:127], v[156:159], v[180:183], v[124:127]
	v_mfma_f32_16x16x32_bf16 v[112:115], v[148:151], v[188:191], v[112:115]
	v_mfma_f32_16x16x32_bf16 v[108:111], v[156:159], v[188:191], v[108:111]
	v_mfma_f32_16x16x32_bf16 v[96:99], v[148:151], v[196:199], v[96:99]
	v_mfma_f32_16x16x32_bf16 v[92:95], v[156:159], v[196:199], v[92:95]
	v_mfma_f32_16x16x32_bf16 v[80:83], v[148:151], v[204:207], v[80:83]
	v_mfma_f32_16x16x32_bf16 v[76:79], v[156:159], v[204:207], v[76:79]
	s_setprio 0
	s_setprio 1
	v_mfma_f32_16x16x32_bf16 v[120:123], v[160:163], v[176:179], v[120:123]
	v_mfma_f32_16x16x32_bf16 v[116:119], v[168:171], v[176:179], v[116:119]
	v_mfma_f32_16x16x32_bf16 v[104:107], v[160:163], v[184:187], v[104:107]
	v_mfma_f32_16x16x32_bf16 v[100:103], v[168:171], v[184:187], v[100:103]
	v_mfma_f32_16x16x32_bf16 v[88:91], v[160:163], v[192:195], v[88:91]
	v_mfma_f32_16x16x32_bf16 v[84:87], v[168:171], v[192:195], v[84:87]
	v_mfma_f32_16x16x32_bf16 v[72:75], v[160:163], v[200:203], v[72:75]
	v_mfma_f32_16x16x32_bf16 v[68:71], v[168:171], v[200:203], v[68:71]
	v_mfma_f32_16x16x32_bf16 v[120:123], v[164:167], v[180:183], v[120:123]
	v_mfma_f32_16x16x32_bf16 v[116:119], v[172:175], v[180:183], v[116:119]
	v_mfma_f32_16x16x32_bf16 v[104:107], v[164:167], v[188:191], v[104:107]
	v_mfma_f32_16x16x32_bf16 v[100:103], v[172:175], v[188:191], v[100:103]
	v_mfma_f32_16x16x32_bf16 v[88:91], v[164:167], v[196:199], v[88:91]
	v_mfma_f32_16x16x32_bf16 v[84:87], v[172:175], v[196:199], v[84:87]
	v_mfma_f32_16x16x32_bf16 v[72:75], v[164:167], v[204:207], v[72:75]
	v_mfma_f32_16x16x32_bf16 v[68:71], v[172:175], v[204:207], v[68:71]
	s_setprio 0
	s_barrier
	s_mov_b32 m0, s66
	v_lshl_add_u64 v[142:143], v[142:143], 0, s[76:77]
	ds_read_b128 v[176:179], v146 offset:49152
	ds_read_b128 v[180:183], v146 offset:50176
	ds_read_b128 v[184:187], v146 offset:51200
	ds_read_b128 v[188:191], v146 offset:52224
	ds_read_b128 v[192:195], v146 offset:53248
	ds_read_b128 v[196:199], v146 offset:54272
	ds_read_b128 v[200:203], v146 offset:55296
	ds_read_b128 v[204:207], v146 offset:56320
	global_load_lds_dwordx4 v[142:143], off
	v_lshl_add_u64 v[142:143], v[208:209], 0, s[76:77]
	s_mov_b32 m0, s65
	s_nop 0
	global_load_lds_dwordx4 v[142:143], off
	s_mov_b32 m0, s74
	s_nop 0
	global_load_lds_dwordx4 v134, s[30:31]
	s_mov_b32 m0, s73
	s_nop 0
	global_load_lds_dwordx4 v0, s[30:31]
	v_lshl_add_u64 v[142:143], v[230:231], 0, s[76:77]
	s_mov_b32 m0, s59
	s_nop 0
	global_load_lds_dwordx4 v[142:143], off
	v_lshl_add_u64 v[142:143], v[232:233], 0, s[76:77]
	s_mov_b32 m0, s60
	s_nop 0
	global_load_lds_dwordx4 v[142:143], off
	s_waitcnt vmcnt(8)
	s_waitcnt lgkmcnt(0)
	s_barrier
	s_setprio 1
	s_waitcnt lgkmcnt(0)
	v_mfma_f32_16x16x32_bf16 v[64:67], v[138:141], v[176:179], v[64:67]
	v_mfma_f32_16x16x32_bf16 v[60:63], v[152:155], v[176:179], v[60:63]
	v_mfma_f32_16x16x32_bf16 v[48:51], v[138:141], v[184:187], v[48:51]
	v_mfma_f32_16x16x32_bf16 v[44:47], v[152:155], v[184:187], v[44:47]
	v_mfma_f32_16x16x32_bf16 v[32:35], v[138:141], v[192:195], v[32:35]
	v_mfma_f32_16x16x32_bf16 v[28:31], v[152:155], v[192:195], v[28:31]
	v_mfma_f32_16x16x32_bf16 v[20:23], v[138:141], v[200:203], v[20:23]
	v_mfma_f32_16x16x32_bf16 v[12:15], v[152:155], v[200:203], v[12:15]
	v_mfma_f32_16x16x32_bf16 v[64:67], v[148:151], v[180:183], v[64:67]
	v_mfma_f32_16x16x32_bf16 v[60:63], v[156:159], v[180:183], v[60:63]
	v_mfma_f32_16x16x32_bf16 v[48:51], v[148:151], v[188:191], v[48:51]
	v_mfma_f32_16x16x32_bf16 v[44:47], v[156:159], v[188:191], v[44:47]
	v_mfma_f32_16x16x32_bf16 v[32:35], v[148:151], v[196:199], v[32:35]
	v_mfma_f32_16x16x32_bf16 v[28:31], v[156:159], v[196:199], v[28:31]
	v_mfma_f32_16x16x32_bf16 v[20:23], v[148:151], v[204:207], v[20:23]
	v_mfma_f32_16x16x32_bf16 v[12:15], v[156:159], v[204:207], v[12:15]
	s_setprio 0
	s_setprio 1
	v_mfma_f32_16x16x32_bf16 v[56:59], v[160:163], v[176:179], v[56:59]
	v_mfma_f32_16x16x32_bf16 v[52:55], v[168:171], v[176:179], v[52:55]
	v_mfma_f32_16x16x32_bf16 v[40:43], v[160:163], v[184:187], v[40:43]
	v_mfma_f32_16x16x32_bf16 v[36:39], v[168:171], v[184:187], v[36:39]
	v_mfma_f32_16x16x32_bf16 v[24:27], v[160:163], v[192:195], v[24:27]
	v_mfma_f32_16x16x32_bf16 v[16:19], v[168:171], v[192:195], v[16:19]
	v_mfma_f32_16x16x32_bf16 v[8:11], v[160:163], v[200:203], v[8:11]
	v_mfma_f32_16x16x32_bf16 v[4:7], v[168:171], v[200:203], v[4:7]
	v_mfma_f32_16x16x32_bf16 v[56:59], v[164:167], v[180:183], v[56:59]
	v_mfma_f32_16x16x32_bf16 v[52:55], v[172:175], v[180:183], v[52:55]
	v_mfma_f32_16x16x32_bf16 v[40:43], v[164:167], v[188:191], v[40:43]
	v_mfma_f32_16x16x32_bf16 v[36:39], v[172:175], v[188:191], v[36:39]
	v_mfma_f32_16x16x32_bf16 v[24:27], v[164:167], v[196:199], v[24:27]
	v_mfma_f32_16x16x32_bf16 v[16:19], v[172:175], v[196:199], v[16:19]
	v_mfma_f32_16x16x32_bf16 v[8:11], v[164:167], v[204:207], v[8:11]
	v_mfma_f32_16x16x32_bf16 v[4:7], v[172:175], v[204:207], v[4:7]
	s_setprio 0
	s_barrier
	s_andn2_b64 vcc, exec, s[28:29]
	s_mov_b64 s[30:31], -1
	s_mov_b64 s[28:29], 0
	s_mov_b64 s[34:35], 0x100
	s_cbranch_vccz .LBB0_1564
	s_and_b64 vcc, exec, s[8:9]
	s_cbranch_vccz .LBB0_1567
	s_barrier

.LBB0_1649:
	s_add_u32 s28, s26, 0xfffc0080
	s_addc_u32 s29, s27, -1
	s_add_i32 s58, 0, 0x10000
	s_cmp_eq_u32 s57, 12
	s_cselect_b32 s31, s19, s29
	s_cselect_b32 s30, s53, s28
	s_cselect_b32 s29, s17, s56
	s_cselect_b32 s28, s54, s55
	s_add_i32 s60, 0, 0x14000
	v_add_u32_e32 v144, s58, v157
	v_add_u32_e32 v159, s60, v157
	ds_read_b128 v[132:135], v144
	ds_read_b128 v[136:139], v144 offset:1024
	ds_read_b128 v[140:143], v144 offset:2048
	ds_read_b128 v[144:147], v144 offset:3072
	ds_read_b128 v[164:167], v159
	ds_read_b128 v[168:171], v159 offset:1024
	ds_read_b128 v[172:175], v159 offset:2048
	ds_read_b128 v[176:179], v159 offset:3072
	s_add_i32 m0, s43, 0xc000
	ds_read_b128 v[180:183], v158
	ds_read_b128 v[184:187], v158 offset:1024
	ds_read_b128 v[188:191], v158 offset:2048
	ds_read_b128 v[192:195], v158 offset:3072
	ds_read_b128 v[196:199], v158 offset:4096
	ds_read_b128 v[200:203], v158 offset:5120
	ds_read_b128 v[204:207], v158 offset:6144
	ds_read_b128 v[230:233], v158 offset:7168
	global_load_lds_dwordx4 v154, s[26:27]
	s_add_i32 m0, s43, 0xe000
	s_nop 0
	global_load_lds_dwordx4 v162, s[26:27]
	s_waitcnt vmcnt(8)
	s_waitcnt lgkmcnt(0)
	s_barrier
	s_setprio 1
	s_waitcnt lgkmcnt(0)
	v_mfma_f32_16x16x32_bf16 v[128:131], v[132:135], v[180:183], v[128:131]
	v_mfma_f32_16x16x32_bf16 v[124:127], v[140:143], v[180:183], v[124:127]
	v_mfma_f32_16x16x32_bf16 v[112:115], v[132:135], v[188:191], v[112:115]
	v_mfma_f32_16x16x32_bf16 v[108:111], v[140:143], v[188:191], v[108:111]
	v_mfma_f32_16x16x32_bf16 v[96:99], v[132:135], v[196:199], v[96:99]
	v_mfma_f32_16x16x32_bf16 v[92:95], v[140:143], v[196:199], v[92:95]
	v_mfma_f32_16x16x32_bf16 v[80:83], v[132:135], v[204:207], v[80:83]
	v_mfma_f32_16x16x32_bf16 v[76:79], v[140:143], v[204:207], v[76:79]
	v_mfma_f32_16x16x32_bf16 v[128:131], v[136:139], v[184:187], v[128:131]
	v_mfma_f32_16x16x32_bf16 v[124:127], v[144:147], v[184:187], v[124:127]
	v_mfma_f32_16x16x32_bf16 v[112:115], v[136:139], v[192:195], v[112:115]
	v_mfma_f32_16x16x32_bf16 v[108:111], v[144:147], v[192:195], v[108:111]
	v_mfma_f32_16x16x32_bf16 v[96:99], v[136:139], v[200:203], v[96:99]
	v_mfma_f32_16x16x32_bf16 v[92:95], v[144:147], v[200:203], v[92:95]
	v_mfma_f32_16x16x32_bf16 v[80:83], v[136:139], v[230:233], v[80:83]
	v_mfma_f32_16x16x32_bf16 v[76:79], v[144:147], v[230:233], v[76:79]
	s_setprio 0
	s_setprio 1
	v_mfma_f32_16x16x32_bf16 v[120:123], v[164:167], v[180:183], v[120:123]
	v_mfma_f32_16x16x32_bf16 v[116:119], v[172:175], v[180:183], v[116:119]
	v_mfma_f32_16x16x32_bf16 v[104:107], v[164:167], v[188:191], v[104:107]
	v_mfma_f32_16x16x32_bf16 v[100:103], v[172:175], v[188:191], v[100:103]
	v_mfma_f32_16x16x32_bf16 v[88:91], v[164:167], v[196:199], v[88:91]
	v_mfma_f32_16x16x32_bf16 v[84:87], v[172:175], v[196:199], v[84:87]
	v_mfma_f32_16x16x32_bf16 v[72:75], v[164:167], v[204:207], v[72:75]
	v_mfma_f32_16x16x32_bf16 v[68:71], v[172:175], v[204:207], v[68:71]
	v_mfma_f32_16x16x32_bf16 v[120:123], v[168:171], v[184:187], v[120:123]
	v_mfma_f32_16x16x32_bf16 v[116:119], v[176:179], v[184:187], v[116:119]
	v_mfma_f32_16x16x32_bf16 v[104:107], v[168:171], v[192:195], v[104:107]
	v_mfma_f32_16x16x32_bf16 v[100:103], v[176:179], v[192:195], v[100:103]
	v_mfma_f32_16x16x32_bf16 v[88:91], v[168:171], v[200:203], v[88:91]
	v_mfma_f32_16x16x32_bf16 v[84:87], v[176:179], v[200:203], v[84:87]
	v_mfma_f32_16x16x32_bf16 v[72:75], v[168:171], v[230:233], v[72:75]
	v_mfma_f32_16x16x32_bf16 v[68:71], v[176:179], v[230:233], v[68:71]
	s_setprio 0
	s_barrier
	s_add_i32 s58, s58, s42
	v_lshl_add_u64 v[160:161], s[28:29], 0, v[150:151]
	s_mov_b32 m0, s58
	ds_read_b128 v[180:183], v158 offset:16384
	ds_read_b128 v[184:187], v158 offset:17408
	ds_read_b128 v[188:191], v158 offset:18432
	ds_read_b128 v[192:195], v158 offset:19456
	ds_read_b128 v[196:199], v158 offset:20480
	ds_read_b128 v[200:203], v158 offset:21504
	ds_read_b128 v[204:207], v158 offset:22528
	ds_read_b128 v[230:233], v158 offset:23552
	global_load_lds_dwordx4 v[160:161], off
	s_add_i32 m0, s58, 0x2000
	s_add_u32 s58, s28, 0x40000
	v_lshl_add_u64 v[208:209], s[28:29], 0, v[0:1]
	s_addc_u32 s59, s29, 0
	s_add_i32 s60, s60, s42
	global_load_lds_dwordx4 v[208:209], off
	s_mov_b32 m0, s60
	v_lshl_add_u64 v[240:241], s[30:31], 0, v[148:149]
	global_load_lds_dwordx4 v150, s[58:59]
	s_add_i32 m0, s60, 0x2000
	s_nop 0
	global_load_lds_dwordx4 v0, s[58:59]
	v_lshl_add_u64 v[234:235], s[30:31], 0, v[152:153]
	s_mov_b32 m0, s43
	s_nop 0
	global_load_lds_dwordx4 v[234:235], off
	s_mov_b32 m0, s44
	s_nop 0
	global_load_lds_dwordx4 v[240:241], off
	s_waitcnt vmcnt(8)
	s_waitcnt lgkmcnt(0)
	s_barrier
	s_setprio 1
	s_waitcnt lgkmcnt(0)
	v_mfma_f32_16x16x32_bf16 v[64:67], v[132:135], v[180:183], v[64:67]
	v_mfma_f32_16x16x32_bf16 v[60:63], v[140:143], v[180:183], v[60:63]
	v_mfma_f32_16x16x32_bf16 v[48:51], v[132:135], v[188:191], v[48:51]
	v_mfma_f32_16x16x32_bf16 v[44:47], v[140:143], v[188:191], v[44:47]
	v_mfma_f32_16x16x32_bf16 v[32:35], v[132:135], v[196:199], v[32:35]
	v_mfma_f32_16x16x32_bf16 v[28:31], v[140:143], v[196:199], v[28:31]
	v_mfma_f32_16x16x32_bf16 v[16:19], v[132:135], v[204:207], v[16:19]
	v_mfma_f32_16x16x32_bf16 v[12:15], v[140:143], v[204:207], v[12:15]
	v_mfma_f32_16x16x32_bf16 v[64:67], v[136:139], v[184:187], v[64:67]
	v_mfma_f32_16x16x32_bf16 v[60:63], v[144:147], v[184:187], v[60:63]
	v_mfma_f32_16x16x32_bf16 v[48:51], v[136:139], v[192:195], v[48:51]
	v_mfma_f32_16x16x32_bf16 v[44:47], v[144:147], v[192:195], v[44:47]
	v_mfma_f32_16x16x32_bf16 v[32:35], v[136:139], v[200:203], v[32:35]
	v_mfma_f32_16x16x32_bf16 v[28:31], v[144:147], v[200:203], v[28:31]
	v_mfma_f32_16x16x32_bf16 v[16:19], v[136:139], v[230:233], v[16:19]
	v_mfma_f32_16x16x32_bf16 v[12:15], v[144:147], v[230:233], v[12:15]
	s_setprio 0
	s_setprio 1
	v_mfma_f32_16x16x32_bf16 v[56:59], v[164:167], v[180:183], v[56:59]
	v_mfma_f32_16x16x32_bf16 v[52:55], v[172:175], v[180:183], v[52:55]
	v_mfma_f32_16x16x32_bf16 v[40:43], v[164:167], v[188:191], v[40:43]
	v_mfma_f32_16x16x32_bf16 v[36:39], v[172:175], v[188:191], v[36:39]
	v_mfma_f32_16x16x32_bf16 v[24:27], v[164:167], v[196:199], v[24:27]
	v_mfma_f32_16x16x32_bf16 v[20:23], v[172:175], v[196:199], v[20:23]
	v_mfma_f32_16x16x32_bf16 v[8:11], v[164:167], v[204:207], v[8:11]
	v_mfma_f32_16x16x32_bf16 v[4:7], v[172:175], v[204:207], v[4:7]
	v_mfma_f32_16x16x32_bf16 v[56:59], v[168:171], v[184:187], v[56:59]
	v_mfma_f32_16x16x32_bf16 v[52:55], v[176:179], v[184:187], v[52:55]
	v_mfma_f32_16x16x32_bf16 v[40:43], v[168:171], v[192:195], v[40:43]
	v_mfma_f32_16x16x32_bf16 v[36:39], v[176:179], v[192:195], v[36:39]
	v_mfma_f32_16x16x32_bf16 v[24:27], v[168:171], v[200:203], v[24:27]
	v_mfma_f32_16x16x32_bf16 v[20:23], v[176:179], v[200:203], v[20:23]
	v_mfma_f32_16x16x32_bf16 v[8:11], v[168:171], v[230:233], v[8:11]
	v_mfma_f32_16x16x32_bf16 v[4:7], v[176:179], v[230:233], v[4:7]
	s_setprio 0
	s_barrier
	s_add_i32 s58, 0, 0x18000
	s_add_i32 s59, 0, 0x1c000
	v_add_u32_e32 v144, s58, v157
	v_add_u32_e32 v159, s59, v157
	ds_read_b128 v[132:135], v144
	ds_read_b128 v[136:139], v144 offset:1024
	ds_read_b128 v[140:143], v144 offset:2048
	ds_read_b128 v[144:147], v144 offset:3072
	ds_read_b128 v[164:167], v159
	ds_read_b128 v[168:171], v159 offset:1024
	ds_read_b128 v[172:175], v159 offset:2048
	ds_read_b128 v[176:179], v159 offset:3072
	s_add_u32 s30, s30, 0x40000
	s_addc_u32 s31, s31, 0
	s_mov_b32 m0, s45
	ds_read_b128 v[180:183], v158 offset:32768
	ds_read_b128 v[184:187], v158 offset:33792
	ds_read_b128 v[188:191], v158 offset:34816
	ds_read_b128 v[192:195], v158 offset:35840
	ds_read_b128 v[196:199], v158 offset:36864
	ds_read_b128 v[200:203], v158 offset:37888
	ds_read_b128 v[204:207], v158 offset:38912
	ds_read_b128 v[230:233], v158 offset:39936
	global_load_lds_dwordx4 v152, s[30:31]
	s_mov_b32 m0, s46
	s_nop 0
	global_load_lds_dwordx4 v148, s[30:31]
	s_waitcnt vmcnt(8)
	s_waitcnt lgkmcnt(0)
	s_barrier
	s_setprio 1
	s_waitcnt lgkmcnt(0)
	v_mfma_f32_16x16x32_bf16 v[128:131], v[132:135], v[180:183], v[128:131]
	v_mfma_f32_16x16x32_bf16 v[124:127], v[140:143], v[180:183], v[124:127]
	v_mfma_f32_16x16x32_bf16 v[112:115], v[132:135], v[188:191], v[112:115]
	v_mfma_f32_16x16x32_bf16 v[108:111], v[140:143], v[188:191], v[108:111]
	v_mfma_f32_16x16x32_bf16 v[96:99], v[132:135], v[196:199], v[96:99]
	v_mfma_f32_16x16x32_bf16 v[92:95], v[140:143], v[196:199], v[92:95]
	v_mfma_f32_16x16x32_bf16 v[80:83], v[132:135], v[204:207], v[80:83]
	v_mfma_f32_16x16x32_bf16 v[76:79], v[140:143], v[204:207], v[76:79]
	v_mfma_f32_16x16x32_bf16 v[128:131], v[136:139], v[184:187], v[128:131]
	v_mfma_f32_16x16x32_bf16 v[124:127], v[144:147], v[184:187], v[124:127]
	v_mfma_f32_16x16x32_bf16 v[112:115], v[136:139], v[192:195], v[112:115]
	v_mfma_f32_16x16x32_bf16 v[108:111], v[144:147], v[192:195], v[108:111]
	v_mfma_f32_16x16x32_bf16 v[96:99], v[136:139], v[200:203], v[96:99]
	v_mfma_f32_16x16x32_bf16 v[92:95], v[144:147], v[200:203], v[92:95]
	v_mfma_f32_16x16x32_bf16 v[80:83], v[136:139], v[230:233], v[80:83]
	v_mfma_f32_16x16x32_bf16 v[76:79], v[144:147], v[230:233], v[76:79]
	s_setprio 0
	s_setprio 1
	v_mfma_f32_16x16x32_bf16 v[120:123], v[164:167], v[180:183], v[120:123]
	v_mfma_f32_16x16x32_bf16 v[116:119], v[172:175], v[180:183], v[116:119]
	v_mfma_f32_16x16x32_bf16 v[104:107], v[164:167], v[188:191], v[104:107]
	v_mfma_f32_16x16x32_bf16 v[100:103], v[172:175], v[188:191], v[100:103]
	v_mfma_f32_16x16x32_bf16 v[88:91], v[164:167], v[196:199], v[88:91]
	v_mfma_f32_16x16x32_bf16 v[84:87], v[172:175], v[196:199], v[84:87]
	v_mfma_f32_16x16x32_bf16 v[72:75], v[164:167], v[204:207], v[72:75]
	v_mfma_f32_16x16x32_bf16 v[68:71], v[172:175], v[204:207], v[68:71]
	v_mfma_f32_16x16x32_bf16 v[120:123], v[168:171], v[184:187], v[120:123]
	v_mfma_f32_16x16x32_bf16 v[116:119], v[176:179], v[184:187], v[116:119]
	v_mfma_f32_16x16x32_bf16 v[104:107], v[168:171], v[192:195], v[104:107]
	v_mfma_f32_16x16x32_bf16 v[100:103], v[176:179], v[192:195], v[100:103]
	v_mfma_f32_16x16x32_bf16 v[88:91], v[168:171], v[200:203], v[88:91]
	v_mfma_f32_16x16x32_bf16 v[84:87], v[176:179], v[200:203], v[84:87]
	v_mfma_f32_16x16x32_bf16 v[72:75], v[168:171], v[230:233], v[72:75]
	v_mfma_f32_16x16x32_bf16 v[68:71], v[176:179], v[230:233], v[68:71]
	s_setprio 0
	s_barrier
	s_add_i32 s30, s58, s42
	v_lshl_add_u64 v[160:161], v[160:161], 0, s[62:63]
	s_mov_b32 m0, s30
	ds_read_b128 v[180:183], v158 offset:49152
	ds_read_b128 v[184:187], v158 offset:50176
	ds_read_b128 v[188:191], v158 offset:51200
	ds_read_b128 v[192:195], v158 offset:52224
	ds_read_b128 v[196:199], v158 offset:53248
	ds_read_b128 v[200:203], v158 offset:54272
	ds_read_b128 v[204:207], v158 offset:55296
	ds_read_b128 v[230:233], v158 offset:56320
	global_load_lds_dwordx4 v[160:161], off
	s_add_i32 m0, s30, 0x2000
	s_add_u32 s28, s28, 0x40080
	v_lshl_add_u64 v[160:161], v[208:209], 0, s[62:63]
	s_addc_u32 s29, s29, 0
	s_add_i32 s30, s59, s42
	global_load_lds_dwordx4 v[160:161], off
	s_mov_b32 m0, s30
	s_nop 0
	global_load_lds_dwordx4 v150, s[28:29]
	s_add_i32 m0, s30, 0x2000
	s_nop 0
	global_load_lds_dwordx4 v0, s[28:29]
	v_lshl_add_u64 v[160:161], v[234:235], 0, s[62:63]
	s_mov_b32 m0, s49
	s_nop 0
	global_load_lds_dwordx4 v[160:161], off
	v_lshl_add_u64 v[160:161], v[240:241], 0, s[62:63]
	s_mov_b32 m0, s50
	s_nop 0
	global_load_lds_dwordx4 v[160:161], off
	s_waitcnt vmcnt(8)
	s_waitcnt lgkmcnt(0)
	s_barrier
	s_setprio 1
	s_waitcnt lgkmcnt(0)
	v_mfma_f32_16x16x32_bf16 v[64:67], v[132:135], v[180:183], v[64:67]
	v_mfma_f32_16x16x32_bf16 v[60:63], v[140:143], v[180:183], v[60:63]
	v_mfma_f32_16x16x32_bf16 v[48:51], v[132:135], v[188:191], v[48:51]
	v_mfma_f32_16x16x32_bf16 v[44:47], v[140:143], v[188:191], v[44:47]
	v_mfma_f32_16x16x32_bf16 v[32:35], v[132:135], v[196:199], v[32:35]
	v_mfma_f32_16x16x32_bf16 v[28:31], v[140:143], v[196:199], v[28:31]
	v_mfma_f32_16x16x32_bf16 v[16:19], v[132:135], v[204:207], v[16:19]
	v_mfma_f32_16x16x32_bf16 v[12:15], v[140:143], v[204:207], v[12:15]
	v_mfma_f32_16x16x32_bf16 v[64:67], v[136:139], v[184:187], v[64:67]
	v_mfma_f32_16x16x32_bf16 v[60:63], v[144:147], v[184:187], v[60:63]
	v_mfma_f32_16x16x32_bf16 v[48:51], v[136:139], v[192:195], v[48:51]
	v_mfma_f32_16x16x32_bf16 v[44:47], v[144:147], v[192:195], v[44:47]
	v_mfma_f32_16x16x32_bf16 v[32:35], v[136:139], v[200:203], v[32:35]
	v_mfma_f32_16x16x32_bf16 v[28:31], v[144:147], v[200:203], v[28:31]
	v_mfma_f32_16x16x32_bf16 v[16:19], v[136:139], v[230:233], v[16:19]
	v_mfma_f32_16x16x32_bf16 v[12:15], v[144:147], v[230:233], v[12:15]
	s_setprio 0
	s_setprio 1
	v_mfma_f32_16x16x32_bf16 v[56:59], v[164:167], v[180:183], v[56:59]
	v_mfma_f32_16x16x32_bf16 v[52:55], v[172:175], v[180:183], v[52:55]
	v_mfma_f32_16x16x32_bf16 v[40:43], v[164:167], v[188:191], v[40:43]
	v_mfma_f32_16x16x32_bf16 v[36:39], v[172:175], v[188:191], v[36:39]
	v_mfma_f32_16x16x32_bf16 v[24:27], v[164:167], v[196:199], v[24:27]
	v_mfma_f32_16x16x32_bf16 v[20:23], v[172:175], v[196:199], v[20:23]
	v_mfma_f32_16x16x32_bf16 v[8:11], v[164:167], v[204:207], v[8:11]
	v_mfma_f32_16x16x32_bf16 v[4:7], v[172:175], v[204:207], v[4:7]
	v_mfma_f32_16x16x32_bf16 v[56:59], v[168:171], v[184:187], v[56:59]
	v_mfma_f32_16x16x32_bf16 v[52:55], v[176:179], v[184:187], v[52:55]
	v_mfma_f32_16x16x32_bf16 v[40:43], v[168:171], v[192:195], v[40:43]
	v_mfma_f32_16x16x32_bf16 v[36:39], v[176:179], v[192:195], v[36:39]
	v_mfma_f32_16x16x32_bf16 v[24:27], v[168:171], v[200:203], v[24:27]
	v_mfma_f32_16x16x32_bf16 v[20:23], v[176:179], v[200:203], v[20:23]
	v_mfma_f32_16x16x32_bf16 v[8:11], v[168:171], v[230:233], v[8:11]
	v_mfma_f32_16x16x32_bf16 v[4:7], v[176:179], v[230:233], v[4:7]
	s_setprio 0
	s_barrier
	s_add_i32 s57, s57, 2
	s_add_u32 s26, s26, 0x100
	s_addc_u32 s27, s27, 0
	s_add_u32 s55, s55, 0x100
	s_addc_u32 s56, s56, 0
	s_cmp_gt_u32 s57, 13
	s_cbranch_scc0 .LBB0_1649
	s_and_b64 vcc, exec, s[8:9]
	s_cbranch_vccz .LBB0_1652
	s_barrier

.LBB0_1738:
	s_add_u32 s30, s4, 0xfffc0080
	s_addc_u32 s31, s5, -1
	s_add_i32 s56, 0, 0x10000
	s_cmp_eq_u32 s55, 12
	s_cselect_b32 s35, s19, s31
	s_cselect_b32 s34, s27, s30
	v_add_u32_e32 v157, s56, v155
	s_cselect_b32 s31, s17, s54
	s_cselect_b32 s30, s52, s53
	s_add_i32 s58, 0, 0x14000
	ds_read_b128 v[132:135], v157
	ds_read_b128 v[136:139], v157 offset:1024
	ds_read_b128 v[150:153], v157 offset:2048
	ds_read_b128 v[158:161], v157 offset:3072
	v_add_u32_e32 v157, s58, v155
	ds_read_b128 v[162:165], v157
	ds_read_b128 v[166:169], v157 offset:1024
	ds_read_b128 v[170:173], v157 offset:2048
	ds_read_b128 v[174:177], v157 offset:3072
	s_add_i32 m0, s29, 0xc000
	ds_read_b128 v[178:181], v156
	ds_read_b128 v[182:185], v156 offset:1024
	ds_read_b128 v[186:189], v156 offset:2048
	ds_read_b128 v[190:193], v156 offset:3072
	ds_read_b128 v[194:197], v156 offset:4096
	ds_read_b128 v[198:201], v156 offset:5120
	ds_read_b128 v[202:205], v156 offset:6144
	ds_read_b128 v[206:209], v156 offset:7168
	global_load_lds_dwordx4 v146, s[4:5]
	s_add_i32 m0, s29, 0xe000
	s_nop 0
	global_load_lds_dwordx4 v148, s[4:5]
	s_waitcnt vmcnt(8)
	s_waitcnt lgkmcnt(0)
	s_barrier
	s_setprio 1
	s_waitcnt lgkmcnt(0)
	v_mfma_f32_16x16x32_bf16 v[128:131], v[132:135], v[178:181], v[128:131]
	v_mfma_f32_16x16x32_bf16 v[124:127], v[150:153], v[178:181], v[124:127]
	v_mfma_f32_16x16x32_bf16 v[112:115], v[132:135], v[186:189], v[112:115]
	v_mfma_f32_16x16x32_bf16 v[108:111], v[150:153], v[186:189], v[108:111]
	v_mfma_f32_16x16x32_bf16 v[96:99], v[132:135], v[194:197], v[96:99]
	v_mfma_f32_16x16x32_bf16 v[92:95], v[150:153], v[194:197], v[92:95]
	v_mfma_f32_16x16x32_bf16 v[80:83], v[132:135], v[202:205], v[80:83]
	v_mfma_f32_16x16x32_bf16 v[76:79], v[150:153], v[202:205], v[76:79]
	v_mfma_f32_16x16x32_bf16 v[128:131], v[136:139], v[182:185], v[128:131]
	v_mfma_f32_16x16x32_bf16 v[124:127], v[158:161], v[182:185], v[124:127]
	v_mfma_f32_16x16x32_bf16 v[112:115], v[136:139], v[190:193], v[112:115]
	v_mfma_f32_16x16x32_bf16 v[108:111], v[158:161], v[190:193], v[108:111]
	v_mfma_f32_16x16x32_bf16 v[96:99], v[136:139], v[198:201], v[96:99]
	v_mfma_f32_16x16x32_bf16 v[92:95], v[158:161], v[198:201], v[92:95]
	v_mfma_f32_16x16x32_bf16 v[80:83], v[136:139], v[206:209], v[80:83]
	v_mfma_f32_16x16x32_bf16 v[76:79], v[158:161], v[206:209], v[76:79]
	s_setprio 0
	s_setprio 1
	v_mfma_f32_16x16x32_bf16 v[120:123], v[162:165], v[178:181], v[120:123]
	v_mfma_f32_16x16x32_bf16 v[116:119], v[170:173], v[178:181], v[116:119]
	v_mfma_f32_16x16x32_bf16 v[104:107], v[162:165], v[186:189], v[104:107]
	v_mfma_f32_16x16x32_bf16 v[100:103], v[170:173], v[186:189], v[100:103]
	v_mfma_f32_16x16x32_bf16 v[88:91], v[162:165], v[194:197], v[88:91]
	v_mfma_f32_16x16x32_bf16 v[84:87], v[170:173], v[194:197], v[84:87]
	v_mfma_f32_16x16x32_bf16 v[72:75], v[162:165], v[202:205], v[72:75]
	v_mfma_f32_16x16x32_bf16 v[68:71], v[170:173], v[202:205], v[68:71]
	v_mfma_f32_16x16x32_bf16 v[120:123], v[166:169], v[182:185], v[120:123]
	v_mfma_f32_16x16x32_bf16 v[116:119], v[174:177], v[182:185], v[116:119]
	v_mfma_f32_16x16x32_bf16 v[104:107], v[166:169], v[190:193], v[104:107]
	v_mfma_f32_16x16x32_bf16 v[100:103], v[174:177], v[190:193], v[100:103]
	v_mfma_f32_16x16x32_bf16 v[88:91], v[166:169], v[198:201], v[88:91]
	v_mfma_f32_16x16x32_bf16 v[84:87], v[174:177], v[198:201], v[84:87]
	v_mfma_f32_16x16x32_bf16 v[72:75], v[166:169], v[206:209], v[72:75]
	v_mfma_f32_16x16x32_bf16 v[68:71], v[174:177], v[206:209], v[68:71]
	s_setprio 0
	s_barrier
	s_add_i32 s56, s56, s43
	v_lshl_add_u64 v[230:231], s[30:31], 0, v[140:141]
	s_mov_b32 m0, s56
	ds_read_b128 v[178:181], v156 offset:16384
	ds_read_b128 v[182:185], v156 offset:17408
	ds_read_b128 v[186:189], v156 offset:18432
	ds_read_b128 v[190:193], v156 offset:19456
	ds_read_b128 v[194:197], v156 offset:20480
	ds_read_b128 v[198:201], v156 offset:21504
	ds_read_b128 v[202:205], v156 offset:22528
	ds_read_b128 v[206:209], v156 offset:23552
	global_load_lds_dwordx4 v[230:231], off
	s_add_i32 m0, s56, 0x2000
	s_add_u32 s56, s30, 0x40000
	v_lshl_add_u64 v[232:233], s[30:31], 0, v[144:145]
	s_addc_u32 s57, s31, 0
	s_add_i32 s58, s58, s43
	global_load_lds_dwordx4 v[232:233], off
	s_mov_b32 m0, s58
	v_lshl_add_u64 v[240:241], s[34:35], 0, v[142:143]
	global_load_lds_dwordx4 v140, s[56:57]
	s_add_i32 m0, s58, 0x2000
	s_nop 0
	global_load_lds_dwordx4 v144, s[56:57]
	v_lshl_add_u64 v[234:235], s[34:35], 0, v[0:1]
	s_mov_b32 m0, s29
	s_nop 0
	global_load_lds_dwordx4 v[234:235], off
	s_mov_b32 m0, s44
	s_nop 0
	global_load_lds_dwordx4 v[240:241], off
	s_waitcnt vmcnt(8)
	s_waitcnt lgkmcnt(0)
	s_barrier
	s_setprio 1
	s_waitcnt lgkmcnt(0)
	v_mfma_f32_16x16x32_bf16 v[64:67], v[132:135], v[178:181], v[64:67]
	v_mfma_f32_16x16x32_bf16 v[60:63], v[150:153], v[178:181], v[60:63]
	v_mfma_f32_16x16x32_bf16 v[48:51], v[132:135], v[186:189], v[48:51]
	v_mfma_f32_16x16x32_bf16 v[44:47], v[150:153], v[186:189], v[44:47]
	v_mfma_f32_16x16x32_bf16 v[32:35], v[132:135], v[194:197], v[32:35]
	v_mfma_f32_16x16x32_bf16 v[28:31], v[150:153], v[194:197], v[28:31]
	v_mfma_f32_16x16x32_bf16 v[16:19], v[132:135], v[202:205], v[16:19]
	v_mfma_f32_16x16x32_bf16 v[12:15], v[150:153], v[202:205], v[12:15]
	v_mfma_f32_16x16x32_bf16 v[64:67], v[136:139], v[182:185], v[64:67]
	v_mfma_f32_16x16x32_bf16 v[60:63], v[158:161], v[182:185], v[60:63]
	v_mfma_f32_16x16x32_bf16 v[48:51], v[136:139], v[190:193], v[48:51]
	v_mfma_f32_16x16x32_bf16 v[44:47], v[158:161], v[190:193], v[44:47]
	v_mfma_f32_16x16x32_bf16 v[32:35], v[136:139], v[198:201], v[32:35]
	v_mfma_f32_16x16x32_bf16 v[28:31], v[158:161], v[198:201], v[28:31]
	v_mfma_f32_16x16x32_bf16 v[16:19], v[136:139], v[206:209], v[16:19]
	v_mfma_f32_16x16x32_bf16 v[12:15], v[158:161], v[206:209], v[12:15]
	s_setprio 0
	s_setprio 1
	v_mfma_f32_16x16x32_bf16 v[56:59], v[162:165], v[178:181], v[56:59]
	v_mfma_f32_16x16x32_bf16 v[52:55], v[170:173], v[178:181], v[52:55]
	v_mfma_f32_16x16x32_bf16 v[40:43], v[162:165], v[186:189], v[40:43]
	v_mfma_f32_16x16x32_bf16 v[36:39], v[170:173], v[186:189], v[36:39]
	v_mfma_f32_16x16x32_bf16 v[24:27], v[162:165], v[194:197], v[24:27]
	v_mfma_f32_16x16x32_bf16 v[20:23], v[170:173], v[194:197], v[20:23]
	v_mfma_f32_16x16x32_bf16 v[8:11], v[162:165], v[202:205], v[8:11]
	v_mfma_f32_16x16x32_bf16 v[4:7], v[170:173], v[202:205], v[4:7]
	v_mfma_f32_16x16x32_bf16 v[56:59], v[166:169], v[182:185], v[56:59]
	v_mfma_f32_16x16x32_bf16 v[52:55], v[174:177], v[182:185], v[52:55]
	v_mfma_f32_16x16x32_bf16 v[40:43], v[166:169], v[190:193], v[40:43]
	v_mfma_f32_16x16x32_bf16 v[36:39], v[174:177], v[190:193], v[36:39]
	v_mfma_f32_16x16x32_bf16 v[24:27], v[166:169], v[198:201], v[24:27]
	v_mfma_f32_16x16x32_bf16 v[20:23], v[174:177], v[198:201], v[20:23]
	v_mfma_f32_16x16x32_bf16 v[8:11], v[166:169], v[206:209], v[8:11]
	v_mfma_f32_16x16x32_bf16 v[4:7], v[174:177], v[206:209], v[4:7]
	s_setprio 0
	s_barrier
	s_add_i32 s56, 0, 0x18000
	v_add_u32_e32 v157, s56, v155
	s_add_i32 s57, 0, 0x1c000
	ds_read_b128 v[132:135], v157
	ds_read_b128 v[136:139], v157 offset:1024
	ds_read_b128 v[150:153], v157 offset:2048
	ds_read_b128 v[158:161], v157 offset:3072
	v_add_u32_e32 v157, s57, v155
	ds_read_b128 v[162:165], v157
	ds_read_b128 v[166:169], v157 offset:1024
	ds_read_b128 v[170:173], v157 offset:2048
	ds_read_b128 v[174:177], v157 offset:3072
	s_add_u32 s34, s34, 0x40000
	s_addc_u32 s35, s35, 0
	s_mov_b32 m0, s45
	ds_read_b128 v[178:181], v156 offset:32768
	ds_read_b128 v[182:185], v156 offset:33792
	ds_read_b128 v[186:189], v156 offset:34816
	ds_read_b128 v[190:193], v156 offset:35840
	ds_read_b128 v[194:197], v156 offset:36864
	ds_read_b128 v[198:201], v156 offset:37888
	ds_read_b128 v[202:205], v156 offset:38912
	ds_read_b128 v[206:209], v156 offset:39936
	global_load_lds_dwordx4 v0, s[34:35]
	s_mov_b32 m0, s46
	s_nop 0
	global_load_lds_dwordx4 v142, s[34:35]
	s_waitcnt vmcnt(8)
	s_waitcnt lgkmcnt(0)
	s_barrier
	s_setprio 1
	s_waitcnt lgkmcnt(0)
	v_mfma_f32_16x16x32_bf16 v[128:131], v[132:135], v[178:181], v[128:131]
	v_mfma_f32_16x16x32_bf16 v[124:127], v[150:153], v[178:181], v[124:127]
	v_mfma_f32_16x16x32_bf16 v[112:115], v[132:135], v[186:189], v[112:115]
	v_mfma_f32_16x16x32_bf16 v[108:111], v[150:153], v[186:189], v[108:111]
	v_mfma_f32_16x16x32_bf16 v[96:99], v[132:135], v[194:197], v[96:99]
	v_mfma_f32_16x16x32_bf16 v[92:95], v[150:153], v[194:197], v[92:95]
	v_mfma_f32_16x16x32_bf16 v[80:83], v[132:135], v[202:205], v[80:83]
	v_mfma_f32_16x16x32_bf16 v[76:79], v[150:153], v[202:205], v[76:79]
	v_mfma_f32_16x16x32_bf16 v[128:131], v[136:139], v[182:185], v[128:131]
	v_mfma_f32_16x16x32_bf16 v[124:127], v[158:161], v[182:185], v[124:127]
	v_mfma_f32_16x16x32_bf16 v[112:115], v[136:139], v[190:193], v[112:115]
	v_mfma_f32_16x16x32_bf16 v[108:111], v[158:161], v[190:193], v[108:111]
	v_mfma_f32_16x16x32_bf16 v[96:99], v[136:139], v[198:201], v[96:99]
	v_mfma_f32_16x16x32_bf16 v[92:95], v[158:161], v[198:201], v[92:95]
	v_mfma_f32_16x16x32_bf16 v[80:83], v[136:139], v[206:209], v[80:83]
	v_mfma_f32_16x16x32_bf16 v[76:79], v[158:161], v[206:209], v[76:79]
	s_setprio 0
	s_setprio 1
	v_mfma_f32_16x16x32_bf16 v[120:123], v[162:165], v[178:181], v[120:123]
	v_mfma_f32_16x16x32_bf16 v[116:119], v[170:173], v[178:181], v[116:119]
	v_mfma_f32_16x16x32_bf16 v[104:107], v[162:165], v[186:189], v[104:107]
	v_mfma_f32_16x16x32_bf16 v[100:103], v[170:173], v[186:189], v[100:103]
	v_mfma_f32_16x16x32_bf16 v[88:91], v[162:165], v[194:197], v[88:91]
	v_mfma_f32_16x16x32_bf16 v[84:87], v[170:173], v[194:197], v[84:87]
	v_mfma_f32_16x16x32_bf16 v[72:75], v[162:165], v[202:205], v[72:75]
	v_mfma_f32_16x16x32_bf16 v[68:71], v[170:173], v[202:205], v[68:71]
	v_mfma_f32_16x16x32_bf16 v[120:123], v[166:169], v[182:185], v[120:123]
	v_mfma_f32_16x16x32_bf16 v[116:119], v[174:177], v[182:185], v[116:119]
	v_mfma_f32_16x16x32_bf16 v[104:107], v[166:169], v[190:193], v[104:107]
	v_mfma_f32_16x16x32_bf16 v[100:103], v[174:177], v[190:193], v[100:103]
	v_mfma_f32_16x16x32_bf16 v[88:91], v[166:169], v[198:201], v[88:91]
	v_mfma_f32_16x16x32_bf16 v[84:87], v[174:177], v[198:201], v[84:87]
	v_mfma_f32_16x16x32_bf16 v[72:75], v[166:169], v[206:209], v[72:75]
	v_mfma_f32_16x16x32_bf16 v[68:71], v[174:177], v[206:209], v[68:71]
	s_setprio 0
	s_barrier
	s_add_i32 s34, s56, s43
	v_lshl_add_u64 v[230:231], v[230:231], 0, s[60:61]
	s_mov_b32 m0, s34
	ds_read_b128 v[178:181], v156 offset:49152
	ds_read_b128 v[182:185], v156 offset:50176
	ds_read_b128 v[186:189], v156 offset:51200
	ds_read_b128 v[190:193], v156 offset:52224
	ds_read_b128 v[194:197], v156 offset:53248
	ds_read_b128 v[198:201], v156 offset:54272
	ds_read_b128 v[202:205], v156 offset:55296
	ds_read_b128 v[206:209], v156 offset:56320
	global_load_lds_dwordx4 v[230:231], off
	s_add_i32 m0, s34, 0x2000
	s_add_u32 s30, s30, 0x40080
	v_lshl_add_u64 v[230:231], v[232:233], 0, s[60:61]
	s_addc_u32 s31, s31, 0
	s_add_i32 s34, s57, s43
	global_load_lds_dwordx4 v[230:231], off
	s_mov_b32 m0, s34
	s_nop 0
	global_load_lds_dwordx4 v140, s[30:31]
	s_add_i32 m0, s34, 0x2000
	s_nop 0
	global_load_lds_dwordx4 v144, s[30:31]
	v_lshl_add_u64 v[230:231], v[234:235], 0, s[60:61]
	s_mov_b32 m0, s49
	s_nop 0
	global_load_lds_dwordx4 v[230:231], off
	v_lshl_add_u64 v[230:231], v[240:241], 0, s[60:61]
	s_mov_b32 m0, s50
	s_nop 0
	global_load_lds_dwordx4 v[230:231], off
	s_waitcnt vmcnt(8)
	s_waitcnt lgkmcnt(0)
	s_barrier
	s_setprio 1
	s_waitcnt lgkmcnt(0)
	v_mfma_f32_16x16x32_bf16 v[64:67], v[132:135], v[178:181], v[64:67]
	v_mfma_f32_16x16x32_bf16 v[60:63], v[150:153], v[178:181], v[60:63]
	v_mfma_f32_16x16x32_bf16 v[48:51], v[132:135], v[186:189], v[48:51]
	v_mfma_f32_16x16x32_bf16 v[44:47], v[150:153], v[186:189], v[44:47]
	v_mfma_f32_16x16x32_bf16 v[32:35], v[132:135], v[194:197], v[32:35]
	v_mfma_f32_16x16x32_bf16 v[28:31], v[150:153], v[194:197], v[28:31]
	v_mfma_f32_16x16x32_bf16 v[16:19], v[132:135], v[202:205], v[16:19]
	v_mfma_f32_16x16x32_bf16 v[12:15], v[150:153], v[202:205], v[12:15]
	v_mfma_f32_16x16x32_bf16 v[64:67], v[136:139], v[182:185], v[64:67]
	v_mfma_f32_16x16x32_bf16 v[60:63], v[158:161], v[182:185], v[60:63]
	v_mfma_f32_16x16x32_bf16 v[48:51], v[136:139], v[190:193], v[48:51]
	v_mfma_f32_16x16x32_bf16 v[44:47], v[158:161], v[190:193], v[44:47]
	v_mfma_f32_16x16x32_bf16 v[32:35], v[136:139], v[198:201], v[32:35]
	v_mfma_f32_16x16x32_bf16 v[28:31], v[158:161], v[198:201], v[28:31]
	v_mfma_f32_16x16x32_bf16 v[16:19], v[136:139], v[206:209], v[16:19]
	v_mfma_f32_16x16x32_bf16 v[12:15], v[158:161], v[206:209], v[12:15]
	s_setprio 0
	s_setprio 1
	v_mfma_f32_16x16x32_bf16 v[56:59], v[162:165], v[178:181], v[56:59]
	v_mfma_f32_16x16x32_bf16 v[52:55], v[170:173], v[178:181], v[52:55]
	v_mfma_f32_16x16x32_bf16 v[40:43], v[162:165], v[186:189], v[40:43]
	v_mfma_f32_16x16x32_bf16 v[36:39], v[170:173], v[186:189], v[36:39]
	v_mfma_f32_16x16x32_bf16 v[24:27], v[162:165], v[194:197], v[24:27]
	v_mfma_f32_16x16x32_bf16 v[20:23], v[170:173], v[194:197], v[20:23]
	v_mfma_f32_16x16x32_bf16 v[8:11], v[162:165], v[202:205], v[8:11]
	v_mfma_f32_16x16x32_bf16 v[4:7], v[170:173], v[202:205], v[4:7]
	v_mfma_f32_16x16x32_bf16 v[56:59], v[166:169], v[182:185], v[56:59]
	v_mfma_f32_16x16x32_bf16 v[52:55], v[174:177], v[182:185], v[52:55]
	v_mfma_f32_16x16x32_bf16 v[40:43], v[166:169], v[190:193], v[40:43]
	v_mfma_f32_16x16x32_bf16 v[36:39], v[174:177], v[190:193], v[36:39]
	v_mfma_f32_16x16x32_bf16 v[24:27], v[166:169], v[198:201], v[24:27]
	v_mfma_f32_16x16x32_bf16 v[20:23], v[174:177], v[198:201], v[20:23]
	v_mfma_f32_16x16x32_bf16 v[8:11], v[166:169], v[206:209], v[8:11]
	v_mfma_f32_16x16x32_bf16 v[4:7], v[174:177], v[206:209], v[4:7]
	s_setprio 0
	s_barrier
	s_add_i32 s55, s55, 2
	s_add_u32 s4, s4, 0x100
	s_addc_u32 s5, s5, 0
	s_add_u32 s53, s53, 0x100
	s_addc_u32 s54, s54, 0
	s_cmp_gt_u32 s55, 13
	s_cbranch_scc0 .LBB0_1738
	s_and_b64 vcc, exec, s[14:15]
	s_cbranch_vccz .LBB0_1741
	s_barrier

.LBB0_1875:
	s_add_u32 s50, s4, 0xfffc0080
	s_addc_u32 s51, s5, -1
	s_add_i32 s75, 0, 0x10000
	s_cmp_eq_u32 s74, 12
	s_cselect_b32 s53, s31, s51
	s_cselect_b32 s52, s37, s50
	v_add_u32_e32 v2, s75, v149
	s_cselect_b32 s51, s29, s73
	s_cselect_b32 s50, s49, s72
	s_add_i32 s78, 0, 0x14000
	ds_read_b128 v[152:155], v2
	ds_read_b128 v[156:159], v2 offset:1024
	ds_read_b128 v[160:163], v2 offset:2048
	ds_read_b128 v[164:167], v2 offset:3072
	v_add_u32_e32 v2, s78, v149
	ds_read_b128 v[168:171], v2
	ds_read_b128 v[172:175], v2 offset:1024
	ds_read_b128 v[176:179], v2 offset:2048
	ds_read_b128 v[180:183], v2 offset:3072
	s_add_i32 m0, s47, 0xc000
	ds_read_b128 v[184:187], v151
	ds_read_b128 v[188:191], v151 offset:1024
	ds_read_b128 v[192:195], v151 offset:2048
	ds_read_b128 v[196:199], v151 offset:3072
	ds_read_b128 v[200:203], v151 offset:4096
	ds_read_b128 v[204:207], v151 offset:5120
	ds_read_b128 v[230:233], v151 offset:6144
	ds_read_b128 v[240:243], v151 offset:7168
	global_load_lds_dwordx4 v138, s[4:5]
	s_add_i32 m0, s47, 0xe000
	s_nop 0
	global_load_lds_dwordx4 v140, s[4:5]
	s_waitcnt vmcnt(8)
	s_waitcnt lgkmcnt(0)
	s_barrier
	s_setprio 1
	s_waitcnt lgkmcnt(0)
	v_mfma_f32_16x16x32_bf16 v[128:131], v[152:155], v[184:187], v[128:131]
	v_mfma_f32_16x16x32_bf16 v[124:127], v[160:163], v[184:187], v[124:127]
	v_mfma_f32_16x16x32_bf16 v[112:115], v[152:155], v[192:195], v[112:115]
	v_mfma_f32_16x16x32_bf16 v[108:111], v[160:163], v[192:195], v[108:111]
	v_mfma_f32_16x16x32_bf16 v[96:99], v[152:155], v[200:203], v[96:99]
	v_mfma_f32_16x16x32_bf16 v[92:95], v[160:163], v[200:203], v[92:95]
	v_mfma_f32_16x16x32_bf16 v[80:83], v[152:155], v[230:233], v[80:83]
	v_mfma_f32_16x16x32_bf16 v[76:79], v[160:163], v[230:233], v[76:79]
	v_mfma_f32_16x16x32_bf16 v[128:131], v[156:159], v[188:191], v[128:131]
	v_mfma_f32_16x16x32_bf16 v[124:127], v[164:167], v[188:191], v[124:127]
	v_mfma_f32_16x16x32_bf16 v[112:115], v[156:159], v[196:199], v[112:115]
	v_mfma_f32_16x16x32_bf16 v[108:111], v[164:167], v[196:199], v[108:111]
	v_mfma_f32_16x16x32_bf16 v[96:99], v[156:159], v[204:207], v[96:99]
	v_mfma_f32_16x16x32_bf16 v[92:95], v[164:167], v[204:207], v[92:95]
	v_mfma_f32_16x16x32_bf16 v[80:83], v[156:159], v[240:243], v[80:83]
	v_mfma_f32_16x16x32_bf16 v[76:79], v[164:167], v[240:243], v[76:79]
	s_setprio 0
	s_setprio 1
	v_mfma_f32_16x16x32_bf16 v[120:123], v[168:171], v[184:187], v[120:123]
	v_mfma_f32_16x16x32_bf16 v[116:119], v[176:179], v[184:187], v[116:119]
	v_mfma_f32_16x16x32_bf16 v[104:107], v[168:171], v[192:195], v[104:107]
	v_mfma_f32_16x16x32_bf16 v[100:103], v[176:179], v[192:195], v[100:103]
	v_mfma_f32_16x16x32_bf16 v[88:91], v[168:171], v[200:203], v[88:91]
	v_mfma_f32_16x16x32_bf16 v[84:87], v[176:179], v[200:203], v[84:87]
	v_mfma_f32_16x16x32_bf16 v[72:75], v[168:171], v[230:233], v[72:75]
	v_mfma_f32_16x16x32_bf16 v[68:71], v[176:179], v[230:233], v[68:71]
	v_mfma_f32_16x16x32_bf16 v[120:123], v[172:175], v[188:191], v[120:123]
	v_mfma_f32_16x16x32_bf16 v[116:119], v[180:183], v[188:191], v[116:119]
	v_mfma_f32_16x16x32_bf16 v[104:107], v[172:175], v[196:199], v[104:107]
	v_mfma_f32_16x16x32_bf16 v[100:103], v[180:183], v[196:199], v[100:103]
	v_mfma_f32_16x16x32_bf16 v[88:91], v[172:175], v[204:207], v[88:91]
	v_mfma_f32_16x16x32_bf16 v[84:87], v[180:183], v[204:207], v[84:87]
	v_mfma_f32_16x16x32_bf16 v[72:75], v[172:175], v[240:243], v[72:75]
	v_mfma_f32_16x16x32_bf16 v[68:71], v[180:183], v[240:243], v[68:71]
	s_setprio 0
	s_barrier
	s_add_i32 s75, s75, s60
	v_lshl_add_u64 v[142:143], s[50:51], 0, v[132:133]
	s_mov_b32 m0, s75
	ds_read_b128 v[184:187], v151 offset:16384
	ds_read_b128 v[188:191], v151 offset:17408
	ds_read_b128 v[192:195], v151 offset:18432
	ds_read_b128 v[196:199], v151 offset:19456
	ds_read_b128 v[200:203], v151 offset:20480
	ds_read_b128 v[204:207], v151 offset:21504
	ds_read_b128 v[230:233], v151 offset:22528
	ds_read_b128 v[240:243], v151 offset:23552
	global_load_lds_dwordx4 v[142:143], off
	s_add_i32 m0, s75, 0x2000
	s_add_u32 s76, s50, 0x40000
	v_lshl_add_u64 v[208:209], s[50:51], 0, v[136:137]
	s_addc_u32 s77, s51, 0
	s_add_i32 s75, s78, s60
	global_load_lds_dwordx4 v[208:209], off
	s_mov_b32 m0, s75
	v_lshl_add_u64 v[244:245], s[52:53], 0, v[134:135]
	global_load_lds_dwordx4 v132, s[76:77]
	s_add_i32 m0, s75, 0x2000
	s_nop 0
	global_load_lds_dwordx4 v136, s[76:77]
	v_lshl_add_u64 v[234:235], s[52:53], 0, v[0:1]
	s_mov_b32 m0, s47
	s_nop 0
	global_load_lds_dwordx4 v[234:235], off
	s_mov_b32 m0, s63
	s_nop 0
	global_load_lds_dwordx4 v[244:245], off
	s_waitcnt vmcnt(8)
	s_waitcnt lgkmcnt(0)
	s_barrier
	s_setprio 1
	s_waitcnt lgkmcnt(0)
	v_mfma_f32_16x16x32_bf16 v[64:67], v[152:155], v[184:187], v[64:67]
	v_mfma_f32_16x16x32_bf16 v[60:63], v[160:163], v[184:187], v[60:63]
	v_mfma_f32_16x16x32_bf16 v[48:51], v[152:155], v[192:195], v[48:51]
	v_mfma_f32_16x16x32_bf16 v[44:47], v[160:163], v[192:195], v[44:47]
	v_mfma_f32_16x16x32_bf16 v[32:35], v[152:155], v[200:203], v[32:35]
	v_mfma_f32_16x16x32_bf16 v[28:31], v[160:163], v[200:203], v[28:31]
	v_mfma_f32_16x16x32_bf16 v[16:19], v[152:155], v[230:233], v[16:19]
	v_mfma_f32_16x16x32_bf16 v[12:15], v[160:163], v[230:233], v[12:15]
	v_mfma_f32_16x16x32_bf16 v[64:67], v[156:159], v[188:191], v[64:67]
	v_mfma_f32_16x16x32_bf16 v[60:63], v[164:167], v[188:191], v[60:63]
	v_mfma_f32_16x16x32_bf16 v[48:51], v[156:159], v[196:199], v[48:51]
	v_mfma_f32_16x16x32_bf16 v[44:47], v[164:167], v[196:199], v[44:47]
	v_mfma_f32_16x16x32_bf16 v[32:35], v[156:159], v[204:207], v[32:35]
	v_mfma_f32_16x16x32_bf16 v[28:31], v[164:167], v[204:207], v[28:31]
	v_mfma_f32_16x16x32_bf16 v[16:19], v[156:159], v[240:243], v[16:19]
	v_mfma_f32_16x16x32_bf16 v[12:15], v[164:167], v[240:243], v[12:15]
	s_setprio 0
	s_setprio 1
	v_mfma_f32_16x16x32_bf16 v[56:59], v[168:171], v[184:187], v[56:59]
	v_mfma_f32_16x16x32_bf16 v[52:55], v[176:179], v[184:187], v[52:55]
	v_mfma_f32_16x16x32_bf16 v[40:43], v[168:171], v[192:195], v[40:43]
	v_mfma_f32_16x16x32_bf16 v[36:39], v[176:179], v[192:195], v[36:39]
	v_mfma_f32_16x16x32_bf16 v[24:27], v[168:171], v[200:203], v[24:27]
	v_mfma_f32_16x16x32_bf16 v[20:23], v[176:179], v[200:203], v[20:23]
	v_mfma_f32_16x16x32_bf16 v[8:11], v[168:171], v[230:233], v[8:11]
	v_mfma_f32_16x16x32_bf16 v[4:7], v[176:179], v[230:233], v[4:7]
	v_mfma_f32_16x16x32_bf16 v[56:59], v[172:175], v[188:191], v[56:59]
	v_mfma_f32_16x16x32_bf16 v[52:55], v[180:183], v[188:191], v[52:55]
	v_mfma_f32_16x16x32_bf16 v[40:43], v[172:175], v[196:199], v[40:43]
	v_mfma_f32_16x16x32_bf16 v[36:39], v[180:183], v[196:199], v[36:39]
	v_mfma_f32_16x16x32_bf16 v[24:27], v[172:175], v[204:207], v[24:27]
	v_mfma_f32_16x16x32_bf16 v[20:23], v[180:183], v[204:207], v[20:23]
	v_mfma_f32_16x16x32_bf16 v[8:11], v[172:175], v[240:243], v[8:11]
	v_mfma_f32_16x16x32_bf16 v[4:7], v[180:183], v[240:243], v[4:7]
	s_setprio 0
	s_barrier
	s_add_i32 s75, 0, 0x18000
	v_add_u32_e32 v2, s75, v149
	s_add_i32 s76, 0, 0x1c000
	ds_read_b128 v[152:155], v2
	ds_read_b128 v[156:159], v2 offset:1024
	ds_read_b128 v[160:163], v2 offset:2048
	ds_read_b128 v[164:167], v2 offset:3072
	v_add_u32_e32 v2, s76, v149
	ds_read_b128 v[168:171], v2
	ds_read_b128 v[172:175], v2 offset:1024
	ds_read_b128 v[176:179], v2 offset:2048
	ds_read_b128 v[180:183], v2 offset:3072
	s_add_u32 s52, s52, 0x40000
	s_addc_u32 s53, s53, 0
	s_mov_b32 m0, s64
	ds_read_b128 v[184:187], v151 offset:32768
	ds_read_b128 v[188:191], v151 offset:33792
	ds_read_b128 v[192:195], v151 offset:34816
	ds_read_b128 v[196:199], v151 offset:35840
	ds_read_b128 v[200:203], v151 offset:36864
	ds_read_b128 v[204:207], v151 offset:37888
	ds_read_b128 v[230:233], v151 offset:38912
	ds_read_b128 v[240:243], v151 offset:39936
	global_load_lds_dwordx4 v0, s[52:53]
	s_mov_b32 m0, s65
	s_nop 0
	global_load_lds_dwordx4 v134, s[52:53]
	s_waitcnt vmcnt(8)
	s_waitcnt lgkmcnt(0)
	s_barrier
	s_setprio 1
	s_waitcnt lgkmcnt(0)
	v_mfma_f32_16x16x32_bf16 v[128:131], v[152:155], v[184:187], v[128:131]
	v_mfma_f32_16x16x32_bf16 v[124:127], v[160:163], v[184:187], v[124:127]
	v_mfma_f32_16x16x32_bf16 v[112:115], v[152:155], v[192:195], v[112:115]
	v_mfma_f32_16x16x32_bf16 v[108:111], v[160:163], v[192:195], v[108:111]
	v_mfma_f32_16x16x32_bf16 v[96:99], v[152:155], v[200:203], v[96:99]
	v_mfma_f32_16x16x32_bf16 v[92:95], v[160:163], v[200:203], v[92:95]
	v_mfma_f32_16x16x32_bf16 v[80:83], v[152:155], v[230:233], v[80:83]
	v_mfma_f32_16x16x32_bf16 v[76:79], v[160:163], v[230:233], v[76:79]
	v_mfma_f32_16x16x32_bf16 v[128:131], v[156:159], v[188:191], v[128:131]
	v_mfma_f32_16x16x32_bf16 v[124:127], v[164:167], v[188:191], v[124:127]
	v_mfma_f32_16x16x32_bf16 v[112:115], v[156:159], v[196:199], v[112:115]
	v_mfma_f32_16x16x32_bf16 v[108:111], v[164:167], v[196:199], v[108:111]
	v_mfma_f32_16x16x32_bf16 v[96:99], v[156:159], v[204:207], v[96:99]
	v_mfma_f32_16x16x32_bf16 v[92:95], v[164:167], v[204:207], v[92:95]
	v_mfma_f32_16x16x32_bf16 v[80:83], v[156:159], v[240:243], v[80:83]
	v_mfma_f32_16x16x32_bf16 v[76:79], v[164:167], v[240:243], v[76:79]
	s_setprio 0
	s_setprio 1
	v_mfma_f32_16x16x32_bf16 v[120:123], v[168:171], v[184:187], v[120:123]
	v_mfma_f32_16x16x32_bf16 v[116:119], v[176:179], v[184:187], v[116:119]
	v_mfma_f32_16x16x32_bf16 v[104:107], v[168:171], v[192:195], v[104:107]
	v_mfma_f32_16x16x32_bf16 v[100:103], v[176:179], v[192:195], v[100:103]
	v_mfma_f32_16x16x32_bf16 v[88:91], v[168:171], v[200:203], v[88:91]
	v_mfma_f32_16x16x32_bf16 v[84:87], v[176:179], v[200:203], v[84:87]
	v_mfma_f32_16x16x32_bf16 v[72:75], v[168:171], v[230:233], v[72:75]
	v_mfma_f32_16x16x32_bf16 v[68:71], v[176:179], v[230:233], v[68:71]
	v_mfma_f32_16x16x32_bf16 v[120:123], v[172:175], v[188:191], v[120:123]
	v_mfma_f32_16x16x32_bf16 v[116:119], v[180:183], v[188:191], v[116:119]
	v_mfma_f32_16x16x32_bf16 v[104:107], v[172:175], v[196:199], v[104:107]
	v_mfma_f32_16x16x32_bf16 v[100:103], v[180:183], v[196:199], v[100:103]
	v_mfma_f32_16x16x32_bf16 v[88:91], v[172:175], v[204:207], v[88:91]
	v_mfma_f32_16x16x32_bf16 v[84:87], v[180:183], v[204:207], v[84:87]
	v_mfma_f32_16x16x32_bf16 v[72:75], v[172:175], v[240:243], v[72:75]
	v_mfma_f32_16x16x32_bf16 v[68:71], v[180:183], v[240:243], v[68:71]
	s_setprio 0
	s_barrier
	s_add_i32 s52, s75, s60
	v_lshl_add_u64 v[142:143], v[142:143], 0, s[82:83]
	s_mov_b32 m0, s52
	ds_read_b128 v[184:187], v151 offset:49152
	ds_read_b128 v[188:191], v151 offset:50176
	ds_read_b128 v[192:195], v151 offset:51200
	ds_read_b128 v[196:199], v151 offset:52224
	ds_read_b128 v[200:203], v151 offset:53248
	ds_read_b128 v[204:207], v151 offset:54272
	ds_read_b128 v[230:233], v151 offset:55296
	ds_read_b128 v[240:243], v151 offset:56320
	global_load_lds_dwordx4 v[142:143], off
	s_add_i32 m0, s52, 0x2000
	s_add_u32 s50, s50, 0x40080
	v_lshl_add_u64 v[142:143], v[208:209], 0, s[82:83]
	s_addc_u32 s51, s51, 0
	s_add_i32 s52, s76, s60
	global_load_lds_dwordx4 v[142:143], off
	s_mov_b32 m0, s52
	s_nop 0
	global_load_lds_dwordx4 v132, s[50:51]
	s_add_i32 m0, s52, 0x2000
	s_nop 0
	global_load_lds_dwordx4 v136, s[50:51]
	v_lshl_add_u64 v[142:143], v[234:235], 0, s[82:83]
	s_mov_b32 m0, s68
	s_nop 0
	global_load_lds_dwordx4 v[142:143], off
	v_lshl_add_u64 v[142:143], v[244:245], 0, s[82:83]
	s_mov_b32 m0, s69
	s_nop 0
	global_load_lds_dwordx4 v[142:143], off
	s_waitcnt vmcnt(8)
	s_waitcnt lgkmcnt(0)
	s_barrier
	s_setprio 1
	s_waitcnt lgkmcnt(0)
	v_mfma_f32_16x16x32_bf16 v[64:67], v[152:155], v[184:187], v[64:67]
	v_mfma_f32_16x16x32_bf16 v[60:63], v[160:163], v[184:187], v[60:63]
	v_mfma_f32_16x16x32_bf16 v[48:51], v[152:155], v[192:195], v[48:51]
	v_mfma_f32_16x16x32_bf16 v[44:47], v[160:163], v[192:195], v[44:47]
	v_mfma_f32_16x16x32_bf16 v[32:35], v[152:155], v[200:203], v[32:35]
	v_mfma_f32_16x16x32_bf16 v[28:31], v[160:163], v[200:203], v[28:31]
	v_mfma_f32_16x16x32_bf16 v[16:19], v[152:155], v[230:233], v[16:19]
	v_mfma_f32_16x16x32_bf16 v[12:15], v[160:163], v[230:233], v[12:15]
	v_mfma_f32_16x16x32_bf16 v[64:67], v[156:159], v[188:191], v[64:67]
	v_mfma_f32_16x16x32_bf16 v[60:63], v[164:167], v[188:191], v[60:63]
	v_mfma_f32_16x16x32_bf16 v[48:51], v[156:159], v[196:199], v[48:51]
	v_mfma_f32_16x16x32_bf16 v[44:47], v[164:167], v[196:199], v[44:47]
	v_mfma_f32_16x16x32_bf16 v[32:35], v[156:159], v[204:207], v[32:35]
	v_mfma_f32_16x16x32_bf16 v[28:31], v[164:167], v[204:207], v[28:31]
	v_mfma_f32_16x16x32_bf16 v[16:19], v[156:159], v[240:243], v[16:19]
	v_mfma_f32_16x16x32_bf16 v[12:15], v[164:167], v[240:243], v[12:15]
	s_setprio 0
	s_setprio 1
	v_mfma_f32_16x16x32_bf16 v[56:59], v[168:171], v[184:187], v[56:59]
	v_mfma_f32_16x16x32_bf16 v[52:55], v[176:179], v[184:187], v[52:55]
	v_mfma_f32_16x16x32_bf16 v[40:43], v[168:171], v[192:195], v[40:43]
	v_mfma_f32_16x16x32_bf16 v[36:39], v[176:179], v[192:195], v[36:39]
	v_mfma_f32_16x16x32_bf16 v[24:27], v[168:171], v[200:203], v[24:27]
	v_mfma_f32_16x16x32_bf16 v[20:23], v[176:179], v[200:203], v[20:23]
	v_mfma_f32_16x16x32_bf16 v[8:11], v[168:171], v[230:233], v[8:11]
	v_mfma_f32_16x16x32_bf16 v[4:7], v[176:179], v[230:233], v[4:7]
	v_mfma_f32_16x16x32_bf16 v[56:59], v[172:175], v[188:191], v[56:59]
	v_mfma_f32_16x16x32_bf16 v[52:55], v[180:183], v[188:191], v[52:55]
	v_mfma_f32_16x16x32_bf16 v[40:43], v[172:175], v[196:199], v[40:43]
	v_mfma_f32_16x16x32_bf16 v[36:39], v[180:183], v[196:199], v[36:39]
	v_mfma_f32_16x16x32_bf16 v[24:27], v[172:175], v[204:207], v[24:27]
	v_mfma_f32_16x16x32_bf16 v[20:23], v[180:183], v[204:207], v[20:23]
	v_mfma_f32_16x16x32_bf16 v[8:11], v[172:175], v[240:243], v[8:11]
	v_mfma_f32_16x16x32_bf16 v[4:7], v[180:183], v[240:243], v[4:7]
	s_setprio 0
	s_barrier
	s_add_i32 s74, s74, 2
	s_add_u32 s4, s4, 0x100
	s_addc_u32 s5, s5, 0
	s_add_u32 s72, s72, 0x100
	s_addc_u32 s73, s73, 0
	s_cmp_gt_u32 s74, 13
	s_cbranch_scc0 .LBB0_1875
	s_and_b64 vcc, exec, s[22:23]
	s_cbranch_vccz .LBB0_1878
	s_barrier

.LBB0_2003:
	s_add_u32 s24, s6, 0x100
	s_addc_u32 s25, s7, 0
	s_add_i32 s55, 0, 0x10000
	s_cmp_eq_u32 s54, 40
	s_cselect_b32 s29, s21, s25
	s_cselect_b32 s28, s20, s24
	v_add_u32_e32 v157, s55, v155
	s_cselect_b32 s27, s23, s53
	s_cselect_b32 s26, s22, s52
	s_add_i32 s56, 0, 0x14000
	ds_read_b128 v[132:135], v157
	ds_read_b128 v[136:139], v157 offset:1024
	ds_read_b128 v[150:153], v157 offset:2048
	ds_read_b128 v[158:161], v157 offset:3072
	v_add_u32_e32 v157, s56, v155
	ds_read_b128 v[162:165], v157
	ds_read_b128 v[166:169], v157 offset:1024
	ds_read_b128 v[170:173], v157 offset:2048
	ds_read_b128 v[174:177], v157 offset:3072
	v_lshl_add_u64 v[230:231], s[6:7], 0, v[146:147]
	s_add_i32 m0, s40, 0xc000
	ds_read_b128 v[178:181], v156
	ds_read_b128 v[182:185], v156 offset:1024
	ds_read_b128 v[186:189], v156 offset:2048
	ds_read_b128 v[190:193], v156 offset:3072
	ds_read_b128 v[194:197], v156 offset:4096
	ds_read_b128 v[198:201], v156 offset:5120
	ds_read_b128 v[202:205], v156 offset:6144
	ds_read_b128 v[206:209], v156 offset:7168
	global_load_lds_dwordx4 v[230:231], off
	v_lshl_add_u64 v[230:231], s[6:7], 0, v[148:149]
	s_add_i32 m0, s40, 0xe000
	s_nop 0
	global_load_lds_dwordx4 v[230:231], off
	s_waitcnt vmcnt(8)
	s_waitcnt lgkmcnt(0)
	s_barrier
	s_setprio 1
	s_waitcnt lgkmcnt(0)
	v_mfma_f32_16x16x32_bf16 v[128:131], v[132:135], v[178:181], v[128:131]
	v_mfma_f32_16x16x32_bf16 v[124:127], v[150:153], v[178:181], v[124:127]
	v_mfma_f32_16x16x32_bf16 v[112:115], v[132:135], v[186:189], v[112:115]
	v_mfma_f32_16x16x32_bf16 v[108:111], v[150:153], v[186:189], v[108:111]
	v_mfma_f32_16x16x32_bf16 v[96:99], v[132:135], v[194:197], v[96:99]
	v_mfma_f32_16x16x32_bf16 v[92:95], v[150:153], v[194:197], v[92:95]
	v_mfma_f32_16x16x32_bf16 v[80:83], v[132:135], v[202:205], v[80:83]
	v_mfma_f32_16x16x32_bf16 v[76:79], v[150:153], v[202:205], v[76:79]
	v_mfma_f32_16x16x32_bf16 v[128:131], v[136:139], v[182:185], v[128:131]
	v_mfma_f32_16x16x32_bf16 v[124:127], v[158:161], v[182:185], v[124:127]
	v_mfma_f32_16x16x32_bf16 v[112:115], v[136:139], v[190:193], v[112:115]
	v_mfma_f32_16x16x32_bf16 v[108:111], v[158:161], v[190:193], v[108:111]
	v_mfma_f32_16x16x32_bf16 v[96:99], v[136:139], v[198:201], v[96:99]
	v_mfma_f32_16x16x32_bf16 v[92:95], v[158:161], v[198:201], v[92:95]
	v_mfma_f32_16x16x32_bf16 v[80:83], v[136:139], v[206:209], v[80:83]
	v_mfma_f32_16x16x32_bf16 v[76:79], v[158:161], v[206:209], v[76:79]
	s_setprio 0
	s_setprio 1
	v_mfma_f32_16x16x32_bf16 v[120:123], v[162:165], v[178:181], v[120:123]
	v_mfma_f32_16x16x32_bf16 v[116:119], v[170:173], v[178:181], v[116:119]
	v_mfma_f32_16x16x32_bf16 v[104:107], v[162:165], v[186:189], v[104:107]
	v_mfma_f32_16x16x32_bf16 v[100:103], v[170:173], v[186:189], v[100:103]
	v_mfma_f32_16x16x32_bf16 v[88:91], v[162:165], v[194:197], v[88:91]
	v_mfma_f32_16x16x32_bf16 v[84:87], v[170:173], v[194:197], v[84:87]
	v_mfma_f32_16x16x32_bf16 v[72:75], v[162:165], v[202:205], v[72:75]
	v_mfma_f32_16x16x32_bf16 v[68:71], v[170:173], v[202:205], v[68:71]
	v_mfma_f32_16x16x32_bf16 v[120:123], v[166:169], v[182:185], v[120:123]
	v_mfma_f32_16x16x32_bf16 v[116:119], v[174:177], v[182:185], v[116:119]
	v_mfma_f32_16x16x32_bf16 v[104:107], v[166:169], v[190:193], v[104:107]
	v_mfma_f32_16x16x32_bf16 v[100:103], v[174:177], v[190:193], v[100:103]
	v_mfma_f32_16x16x32_bf16 v[88:91], v[166:169], v[198:201], v[88:91]
	v_mfma_f32_16x16x32_bf16 v[84:87], v[174:177], v[198:201], v[84:87]
	v_mfma_f32_16x16x32_bf16 v[72:75], v[166:169], v[206:209], v[72:75]
	v_mfma_f32_16x16x32_bf16 v[68:71], v[174:177], v[206:209], v[68:71]
	s_setprio 0
	s_barrier
	s_add_i32 s6, s55, s39
	v_lshl_add_u64 v[230:231], s[26:27], 0, v[140:141]
	s_mov_b32 m0, s6
	ds_read_b128 v[178:181], v156 offset:16384
	ds_read_b128 v[182:185], v156 offset:17408
	ds_read_b128 v[186:189], v156 offset:18432
	ds_read_b128 v[190:193], v156 offset:19456
	ds_read_b128 v[194:197], v156 offset:20480
	ds_read_b128 v[198:201], v156 offset:21504
	ds_read_b128 v[202:205], v156 offset:22528
	ds_read_b128 v[206:209], v156 offset:23552
	global_load_lds_dwordx4 v[230:231], off
	s_add_i32 m0, s6, 0x2000
	s_add_u32 s6, s26, 0xb0000
	v_lshl_add_u64 v[232:233], s[26:27], 0, v[144:145]
	s_addc_u32 s7, s27, 0
	s_add_i32 s55, s56, s39
	global_load_lds_dwordx4 v[232:233], off
	s_mov_b32 m0, s55
	v_lshl_add_u64 v[240:241], s[28:29], 0, v[142:143]
	global_load_lds_dwordx4 v140, s[6:7]
	s_add_i32 m0, s55, 0x2000
	s_nop 0
	global_load_lds_dwordx4 v144, s[6:7]
	v_lshl_add_u64 v[234:235], s[28:29], 0, v[0:1]
	s_mov_b32 m0, s40
	s_nop 0
	global_load_lds_dwordx4 v[234:235], off
	s_mov_b32 m0, s41
	s_nop 0
	global_load_lds_dwordx4 v[240:241], off
	s_waitcnt vmcnt(8)
	s_waitcnt lgkmcnt(0)
	s_barrier
	s_setprio 1
	s_waitcnt lgkmcnt(0)
	v_mfma_f32_16x16x32_bf16 v[64:67], v[132:135], v[178:181], v[64:67]
	v_mfma_f32_16x16x32_bf16 v[60:63], v[150:153], v[178:181], v[60:63]
	v_mfma_f32_16x16x32_bf16 v[48:51], v[132:135], v[186:189], v[48:51]
	v_mfma_f32_16x16x32_bf16 v[44:47], v[150:153], v[186:189], v[44:47]
	v_mfma_f32_16x16x32_bf16 v[32:35], v[132:135], v[194:197], v[32:35]
	v_mfma_f32_16x16x32_bf16 v[28:31], v[150:153], v[194:197], v[28:31]
	v_mfma_f32_16x16x32_bf16 v[16:19], v[132:135], v[202:205], v[16:19]
	v_mfma_f32_16x16x32_bf16 v[12:15], v[150:153], v[202:205], v[12:15]
	v_mfma_f32_16x16x32_bf16 v[64:67], v[136:139], v[182:185], v[64:67]
	v_mfma_f32_16x16x32_bf16 v[60:63], v[158:161], v[182:185], v[60:63]
	v_mfma_f32_16x16x32_bf16 v[48:51], v[136:139], v[190:193], v[48:51]
	v_mfma_f32_16x16x32_bf16 v[44:47], v[158:161], v[190:193], v[44:47]
	v_mfma_f32_16x16x32_bf16 v[32:35], v[136:139], v[198:201], v[32:35]
	v_mfma_f32_16x16x32_bf16 v[28:31], v[158:161], v[198:201], v[28:31]
	v_mfma_f32_16x16x32_bf16 v[16:19], v[136:139], v[206:209], v[16:19]
	v_mfma_f32_16x16x32_bf16 v[12:15], v[158:161], v[206:209], v[12:15]
	s_setprio 0
	s_setprio 1
	v_mfma_f32_16x16x32_bf16 v[56:59], v[162:165], v[178:181], v[56:59]
	v_mfma_f32_16x16x32_bf16 v[52:55], v[170:173], v[178:181], v[52:55]
	v_mfma_f32_16x16x32_bf16 v[40:43], v[162:165], v[186:189], v[40:43]
	v_mfma_f32_16x16x32_bf16 v[36:39], v[170:173], v[186:189], v[36:39]
	v_mfma_f32_16x16x32_bf16 v[24:27], v[162:165], v[194:197], v[24:27]
	v_mfma_f32_16x16x32_bf16 v[20:23], v[170:173], v[194:197], v[20:23]
	v_mfma_f32_16x16x32_bf16 v[8:11], v[162:165], v[202:205], v[8:11]
	v_mfma_f32_16x16x32_bf16 v[4:7], v[170:173], v[202:205], v[4:7]
	v_mfma_f32_16x16x32_bf16 v[56:59], v[166:169], v[182:185], v[56:59]
	v_mfma_f32_16x16x32_bf16 v[52:55], v[174:177], v[182:185], v[52:55]
	v_mfma_f32_16x16x32_bf16 v[40:43], v[166:169], v[190:193], v[40:43]
	v_mfma_f32_16x16x32_bf16 v[36:39], v[174:177], v[190:193], v[36:39]
	v_mfma_f32_16x16x32_bf16 v[24:27], v[166:169], v[198:201], v[24:27]
	v_mfma_f32_16x16x32_bf16 v[20:23], v[174:177], v[198:201], v[20:23]
	v_mfma_f32_16x16x32_bf16 v[8:11], v[166:169], v[206:209], v[8:11]
	v_mfma_f32_16x16x32_bf16 v[4:7], v[174:177], v[206:209], v[4:7]
	s_setprio 0
	s_barrier
	s_add_i32 s55, 0, 0x18000
	v_add_u32_e32 v157, s55, v155
	s_add_i32 s56, 0, 0x1c000
	ds_read_b128 v[132:135], v157
	ds_read_b128 v[136:139], v157 offset:1024
	ds_read_b128 v[150:153], v157 offset:2048
	ds_read_b128 v[158:161], v157 offset:3072
	v_add_u32_e32 v157, s56, v155
	ds_read_b128 v[162:165], v157
	ds_read_b128 v[166:169], v157 offset:1024
	ds_read_b128 v[170:173], v157 offset:2048
	ds_read_b128 v[174:177], v157 offset:3072
	s_add_u32 s6, s28, 0xb0000
	s_addc_u32 s7, s29, 0
	s_mov_b32 m0, s42
	ds_read_b128 v[178:181], v156 offset:32768
	ds_read_b128 v[182:185], v156 offset:33792
	ds_read_b128 v[186:189], v156 offset:34816
	ds_read_b128 v[190:193], v156 offset:35840
	ds_read_b128 v[194:197], v156 offset:36864
	ds_read_b128 v[198:201], v156 offset:37888
	ds_read_b128 v[202:205], v156 offset:38912
	ds_read_b128 v[206:209], v156 offset:39936
	global_load_lds_dwordx4 v0, s[6:7]
	s_mov_b32 m0, s43
	s_nop 0
	global_load_lds_dwordx4 v142, s[6:7]
	s_waitcnt vmcnt(8)
	s_waitcnt lgkmcnt(0)
	s_barrier
	s_setprio 1
	s_waitcnt lgkmcnt(0)
	v_mfma_f32_16x16x32_bf16 v[128:131], v[132:135], v[178:181], v[128:131]
	v_mfma_f32_16x16x32_bf16 v[124:127], v[150:153], v[178:181], v[124:127]
	v_mfma_f32_16x16x32_bf16 v[112:115], v[132:135], v[186:189], v[112:115]
	v_mfma_f32_16x16x32_bf16 v[108:111], v[150:153], v[186:189], v[108:111]
	v_mfma_f32_16x16x32_bf16 v[96:99], v[132:135], v[194:197], v[96:99]
	v_mfma_f32_16x16x32_bf16 v[92:95], v[150:153], v[194:197], v[92:95]
	v_mfma_f32_16x16x32_bf16 v[80:83], v[132:135], v[202:205], v[80:83]
	v_mfma_f32_16x16x32_bf16 v[76:79], v[150:153], v[202:205], v[76:79]
	v_mfma_f32_16x16x32_bf16 v[128:131], v[136:139], v[182:185], v[128:131]
	v_mfma_f32_16x16x32_bf16 v[124:127], v[158:161], v[182:185], v[124:127]
	v_mfma_f32_16x16x32_bf16 v[112:115], v[136:139], v[190:193], v[112:115]
	v_mfma_f32_16x16x32_bf16 v[108:111], v[158:161], v[190:193], v[108:111]
	v_mfma_f32_16x16x32_bf16 v[96:99], v[136:139], v[198:201], v[96:99]
	v_mfma_f32_16x16x32_bf16 v[92:95], v[158:161], v[198:201], v[92:95]
	v_mfma_f32_16x16x32_bf16 v[80:83], v[136:139], v[206:209], v[80:83]
	v_mfma_f32_16x16x32_bf16 v[76:79], v[158:161], v[206:209], v[76:79]
	s_setprio 0
	s_setprio 1
	v_mfma_f32_16x16x32_bf16 v[120:123], v[162:165], v[178:181], v[120:123]
	v_mfma_f32_16x16x32_bf16 v[116:119], v[170:173], v[178:181], v[116:119]
	v_mfma_f32_16x16x32_bf16 v[104:107], v[162:165], v[186:189], v[104:107]
	v_mfma_f32_16x16x32_bf16 v[100:103], v[170:173], v[186:189], v[100:103]
	v_mfma_f32_16x16x32_bf16 v[88:91], v[162:165], v[194:197], v[88:91]
	v_mfma_f32_16x16x32_bf16 v[84:87], v[170:173], v[194:197], v[84:87]
	v_mfma_f32_16x16x32_bf16 v[72:75], v[162:165], v[202:205], v[72:75]
	v_mfma_f32_16x16x32_bf16 v[68:71], v[170:173], v[202:205], v[68:71]
	v_mfma_f32_16x16x32_bf16 v[120:123], v[166:169], v[182:185], v[120:123]
	v_mfma_f32_16x16x32_bf16 v[116:119], v[174:177], v[182:185], v[116:119]
	v_mfma_f32_16x16x32_bf16 v[104:107], v[166:169], v[190:193], v[104:107]
	v_mfma_f32_16x16x32_bf16 v[100:103], v[174:177], v[190:193], v[100:103]
	v_mfma_f32_16x16x32_bf16 v[88:91], v[166:169], v[198:201], v[88:91]
	v_mfma_f32_16x16x32_bf16 v[84:87], v[174:177], v[198:201], v[84:87]
	v_mfma_f32_16x16x32_bf16 v[72:75], v[166:169], v[206:209], v[72:75]
	v_mfma_f32_16x16x32_bf16 v[68:71], v[174:177], v[206:209], v[68:71]
	s_setprio 0
	s_barrier
	s_add_i32 s6, s55, s39
	v_lshl_add_u64 v[230:231], v[230:231], 0, s[58:59]
	s_mov_b32 m0, s6
	ds_read_b128 v[178:181], v156 offset:49152
	ds_read_b128 v[182:185], v156 offset:50176
	ds_read_b128 v[186:189], v156 offset:51200
	ds_read_b128 v[190:193], v156 offset:52224
	ds_read_b128 v[194:197], v156 offset:53248
	ds_read_b128 v[198:201], v156 offset:54272
	ds_read_b128 v[202:205], v156 offset:55296
	ds_read_b128 v[206:209], v156 offset:56320
	global_load_lds_dwordx4 v[230:231], off
	s_add_i32 m0, s6, 0x2000
	s_add_u32 s6, s26, 0xb0080
	v_lshl_add_u64 v[230:231], v[232:233], 0, s[58:59]
	s_addc_u32 s7, s27, 0
	s_add_i32 s26, s56, s39
	global_load_lds_dwordx4 v[230:231], off
	s_mov_b32 m0, s26
	s_nop 0
	global_load_lds_dwordx4 v140, s[6:7]
	s_add_i32 m0, s26, 0x2000
	s_nop 0
	global_load_lds_dwordx4 v144, s[6:7]
	v_lshl_add_u64 v[230:231], v[234:235], 0, s[58:59]
	s_mov_b32 m0, s45
	s_nop 0
	global_load_lds_dwordx4 v[230:231], off
	v_lshl_add_u64 v[230:231], v[240:241], 0, s[58:59]
	s_mov_b32 m0, s46
	s_nop 0
	global_load_lds_dwordx4 v[230:231], off
	s_waitcnt vmcnt(8)
	s_waitcnt lgkmcnt(0)
	s_barrier
	s_setprio 1
	s_waitcnt lgkmcnt(0)
	v_mfma_f32_16x16x32_bf16 v[64:67], v[132:135], v[178:181], v[64:67]
	v_mfma_f32_16x16x32_bf16 v[60:63], v[150:153], v[178:181], v[60:63]
	v_mfma_f32_16x16x32_bf16 v[48:51], v[132:135], v[186:189], v[48:51]
	v_mfma_f32_16x16x32_bf16 v[44:47], v[150:153], v[186:189], v[44:47]
	v_mfma_f32_16x16x32_bf16 v[32:35], v[132:135], v[194:197], v[32:35]
	v_mfma_f32_16x16x32_bf16 v[28:31], v[150:153], v[194:197], v[28:31]
	v_mfma_f32_16x16x32_bf16 v[16:19], v[132:135], v[202:205], v[16:19]
	v_mfma_f32_16x16x32_bf16 v[12:15], v[150:153], v[202:205], v[12:15]
	v_mfma_f32_16x16x32_bf16 v[64:67], v[136:139], v[182:185], v[64:67]
	v_mfma_f32_16x16x32_bf16 v[60:63], v[158:161], v[182:185], v[60:63]
	v_mfma_f32_16x16x32_bf16 v[48:51], v[136:139], v[190:193], v[48:51]
	v_mfma_f32_16x16x32_bf16 v[44:47], v[158:161], v[190:193], v[44:47]
	v_mfma_f32_16x16x32_bf16 v[32:35], v[136:139], v[198:201], v[32:35]
	v_mfma_f32_16x16x32_bf16 v[28:31], v[158:161], v[198:201], v[28:31]
	v_mfma_f32_16x16x32_bf16 v[16:19], v[136:139], v[206:209], v[16:19]
	v_mfma_f32_16x16x32_bf16 v[12:15], v[158:161], v[206:209], v[12:15]
	s_setprio 0
	s_setprio 1
	v_mfma_f32_16x16x32_bf16 v[56:59], v[162:165], v[178:181], v[56:59]
	v_mfma_f32_16x16x32_bf16 v[52:55], v[170:173], v[178:181], v[52:55]
	v_mfma_f32_16x16x32_bf16 v[40:43], v[162:165], v[186:189], v[40:43]
	v_mfma_f32_16x16x32_bf16 v[36:39], v[170:173], v[186:189], v[36:39]
	v_mfma_f32_16x16x32_bf16 v[24:27], v[162:165], v[194:197], v[24:27]
	v_mfma_f32_16x16x32_bf16 v[20:23], v[170:173], v[194:197], v[20:23]
	v_mfma_f32_16x16x32_bf16 v[8:11], v[162:165], v[202:205], v[8:11]
	v_mfma_f32_16x16x32_bf16 v[4:7], v[170:173], v[202:205], v[4:7]
	v_mfma_f32_16x16x32_bf16 v[56:59], v[166:169], v[182:185], v[56:59]
	v_mfma_f32_16x16x32_bf16 v[52:55], v[174:177], v[182:185], v[52:55]
	v_mfma_f32_16x16x32_bf16 v[40:43], v[166:169], v[190:193], v[40:43]
	v_mfma_f32_16x16x32_bf16 v[36:39], v[174:177], v[190:193], v[36:39]
	v_mfma_f32_16x16x32_bf16 v[24:27], v[166:169], v[198:201], v[24:27]
	v_mfma_f32_16x16x32_bf16 v[20:23], v[174:177], v[198:201], v[20:23]
	v_mfma_f32_16x16x32_bf16 v[8:11], v[166:169], v[206:209], v[8:11]
	v_mfma_f32_16x16x32_bf16 v[4:7], v[174:177], v[206:209], v[4:7]
	s_setprio 0
	s_barrier
	s_add_i32 s54, s54, 2
	s_add_u32 s52, s52, 0x100
	s_addc_u32 s53, s53, 0
	s_cmp_gt_u32 s54, 41
	s_mov_b64 s[6:7], s[24:25]
	s_cbranch_scc0 .LBB0_2003
	s_and_b64 vcc, exec, s[18:19]
	s_cbranch_vccz .LBB0_2006
	s_barrier
